# skip redundant first accumulator-zeroing block (128 v_mov per GEMM unit) in all 9 GEMM phases
# speedup vs baseline: 1.0042x; 1.0042x over previous
.LBB0_224:
	s_andn2_b64 vcc, exec, s[18:19]
	s_cbranch_vccz .Lzskip_1
	v_mov_b32_e32 v123, 0
	v_mov_b32_e32 v122, v123
	v_mov_b32_e32 v121, v123
	v_mov_b32_e32 v120, v123
	v_mov_b32_e32 v119, v123
	v_mov_b32_e32 v118, v123
	v_mov_b32_e32 v117, v123
	v_mov_b32_e32 v116, v123
	v_mov_b32_e32 v111, v123
	v_mov_b32_e32 v110, v123
	v_mov_b32_e32 v109, v123
	v_mov_b32_e32 v108, v123
	v_mov_b32_e32 v103, v123
	v_mov_b32_e32 v102, v123
	v_mov_b32_e32 v101, v123
	v_mov_b32_e32 v100, v123
	v_mov_b32_e32 v95, v123
	v_mov_b32_e32 v94, v123
	v_mov_b32_e32 v93, v123
	v_mov_b32_e32 v92, v123
	v_mov_b32_e32 v87, v123
	v_mov_b32_e32 v86, v123
	v_mov_b32_e32 v85, v123
	v_mov_b32_e32 v84, v123
	v_mov_b32_e32 v79, v123
	v_mov_b32_e32 v78, v123
	v_mov_b32_e32 v77, v123
	v_mov_b32_e32 v76, v123
	v_mov_b32_e32 v71, v123
	v_mov_b32_e32 v70, v123
	v_mov_b32_e32 v69, v123
	v_mov_b32_e32 v68, v123
	v_mov_b32_e32 v127, v123
	v_mov_b32_e32 v126, v123
	v_mov_b32_e32 v125, v123
	v_mov_b32_e32 v124, v123
	v_mov_b32_e32 v115, v123
	v_mov_b32_e32 v114, v123
	v_mov_b32_e32 v113, v123
	v_mov_b32_e32 v112, v123
	v_mov_b32_e32 v107, v123
	v_mov_b32_e32 v106, v123
	v_mov_b32_e32 v105, v123
	v_mov_b32_e32 v104, v123
	v_mov_b32_e32 v99, v123
	v_mov_b32_e32 v98, v123
	v_mov_b32_e32 v97, v123
	v_mov_b32_e32 v96, v123
	v_mov_b32_e32 v91, v123
	v_mov_b32_e32 v90, v123
	v_mov_b32_e32 v89, v123
	v_mov_b32_e32 v88, v123
	v_mov_b32_e32 v83, v123
	v_mov_b32_e32 v82, v123
	v_mov_b32_e32 v81, v123
	v_mov_b32_e32 v80, v123
	v_mov_b32_e32 v75, v123
	v_mov_b32_e32 v74, v123
	v_mov_b32_e32 v73, v123
	v_mov_b32_e32 v72, v123
	v_mov_b32_e32 v67, v123
	v_mov_b32_e32 v66, v123
	v_mov_b32_e32 v65, v123
	v_mov_b32_e32 v64, v123
	v_mov_b32_e32 v63, v123
	v_mov_b32_e32 v62, v123
	v_mov_b32_e32 v61, v123
	v_mov_b32_e32 v60, v123
	v_mov_b32_e32 v55, v123
	v_mov_b32_e32 v54, v123
	v_mov_b32_e32 v53, v123
	v_mov_b32_e32 v52, v123
	v_mov_b32_e32 v47, v123
	v_mov_b32_e32 v46, v123
	v_mov_b32_e32 v45, v123
	v_mov_b32_e32 v44, v123
	v_mov_b32_e32 v39, v123
	v_mov_b32_e32 v38, v123
	v_mov_b32_e32 v37, v123
	v_mov_b32_e32 v36, v123
	v_mov_b32_e32 v31, v123
	v_mov_b32_e32 v30, v123
	v_mov_b32_e32 v29, v123
	v_mov_b32_e32 v28, v123
	v_mov_b32_e32 v23, v123
	v_mov_b32_e32 v22, v123
	v_mov_b32_e32 v21, v123
	v_mov_b32_e32 v20, v123
	v_mov_b32_e32 v15, v123
	v_mov_b32_e32 v14, v123
	v_mov_b32_e32 v13, v123
	v_mov_b32_e32 v12, v123
	v_mov_b32_e32 v7, v123
	v_mov_b32_e32 v6, v123
	v_mov_b32_e32 v5, v123
	v_mov_b32_e32 v4, v123
	v_mov_b32_e32 v59, v123
	v_mov_b32_e32 v58, v123
	v_mov_b32_e32 v57, v123
	v_mov_b32_e32 v56, v123
	v_mov_b32_e32 v51, v123
	v_mov_b32_e32 v50, v123
	v_mov_b32_e32 v49, v123
	v_mov_b32_e32 v48, v123
	v_mov_b32_e32 v43, v123
	v_mov_b32_e32 v42, v123
	v_mov_b32_e32 v41, v123
	v_mov_b32_e32 v40, v123
	v_mov_b32_e32 v35, v123
	v_mov_b32_e32 v34, v123
	v_mov_b32_e32 v33, v123
	v_mov_b32_e32 v32, v123
	v_mov_b32_e32 v27, v123
	v_mov_b32_e32 v26, v123
	v_mov_b32_e32 v25, v123
	v_mov_b32_e32 v24, v123
	v_mov_b32_e32 v19, v123
	v_mov_b32_e32 v18, v123
	v_mov_b32_e32 v17, v123
	v_mov_b32_e32 v16, v123
	v_mov_b32_e32 v11, v123
	v_mov_b32_e32 v10, v123
	v_mov_b32_e32 v9, v123
	v_mov_b32_e32 v8, v123
	v_mov_b32_e32 v3, v123
	v_mov_b32_e32 v2, v123
	v_mov_b32_e32 v1, v123
	v_mov_b32_e32 v0, v123
	s_branch .LBB0_227
.Lzskip_1:
	s_add_u32 s0, s6, 0x80
	s_addc_u32 s1, s7, 0
	s_add_u32 s6, s4, 0x100
	v_mov_b32_e32 v0, 0
	s_addc_u32 s7, s5, 0
	s_mov_b32 s4, 0
	v_mov_b32_e32 v1, v0
	v_mov_b32_e32 v2, v0
	v_mov_b32_e32 v3, v0
	v_mov_b32_e32 v8, v0
	v_mov_b32_e32 v9, v0
	v_mov_b32_e32 v10, v0
	v_mov_b32_e32 v11, v0
	v_mov_b32_e32 v16, v0
	v_mov_b32_e32 v17, v0
	v_mov_b32_e32 v18, v0
	v_mov_b32_e32 v19, v0
	v_mov_b32_e32 v24, v0
	v_mov_b32_e32 v25, v0
	v_mov_b32_e32 v26, v0
	v_mov_b32_e32 v27, v0
	v_mov_b32_e32 v32, v0
	v_mov_b32_e32 v33, v0
	v_mov_b32_e32 v34, v0
	v_mov_b32_e32 v35, v0
	v_mov_b32_e32 v40, v0
	v_mov_b32_e32 v41, v0
	v_mov_b32_e32 v42, v0
	v_mov_b32_e32 v43, v0
	v_mov_b32_e32 v48, v0
	v_mov_b32_e32 v49, v0
	v_mov_b32_e32 v50, v0
	v_mov_b32_e32 v51, v0
	v_mov_b32_e32 v56, v0
	v_mov_b32_e32 v57, v0
	v_mov_b32_e32 v58, v0
	v_mov_b32_e32 v59, v0
	v_mov_b32_e32 v4, v0
	v_mov_b32_e32 v5, v0
	v_mov_b32_e32 v6, v0
	v_mov_b32_e32 v7, v0
	v_mov_b32_e32 v12, v0
	v_mov_b32_e32 v13, v0
	v_mov_b32_e32 v14, v0
	v_mov_b32_e32 v15, v0
	v_mov_b32_e32 v20, v0
	v_mov_b32_e32 v21, v0
	v_mov_b32_e32 v22, v0
	v_mov_b32_e32 v23, v0
	v_mov_b32_e32 v28, v0
	v_mov_b32_e32 v29, v0
	v_mov_b32_e32 v30, v0
	v_mov_b32_e32 v31, v0
	v_mov_b32_e32 v36, v0
	v_mov_b32_e32 v37, v0
	v_mov_b32_e32 v38, v0
	v_mov_b32_e32 v39, v0
	v_mov_b32_e32 v44, v0
	v_mov_b32_e32 v45, v0
	v_mov_b32_e32 v46, v0
	v_mov_b32_e32 v47, v0
	v_mov_b32_e32 v52, v0
	v_mov_b32_e32 v53, v0
	v_mov_b32_e32 v54, v0
	v_mov_b32_e32 v55, v0
	v_mov_b32_e32 v60, v0
	v_mov_b32_e32 v61, v0
	v_mov_b32_e32 v62, v0
	v_mov_b32_e32 v63, v0
	v_mov_b32_e32 v64, v0
	v_mov_b32_e32 v65, v0
	v_mov_b32_e32 v66, v0
	v_mov_b32_e32 v67, v0
	v_mov_b32_e32 v72, v0
	v_mov_b32_e32 v73, v0
	v_mov_b32_e32 v74, v0
	v_mov_b32_e32 v75, v0
	v_mov_b32_e32 v80, v0
	v_mov_b32_e32 v81, v0
	v_mov_b32_e32 v82, v0
	v_mov_b32_e32 v83, v0
	v_mov_b32_e32 v88, v0
	v_mov_b32_e32 v89, v0
	v_mov_b32_e32 v90, v0
	v_mov_b32_e32 v91, v0
	v_mov_b32_e32 v96, v0
	v_mov_b32_e32 v97, v0
	v_mov_b32_e32 v98, v0
	v_mov_b32_e32 v99, v0
	v_mov_b32_e32 v104, v0
	v_mov_b32_e32 v105, v0
	v_mov_b32_e32 v106, v0
	v_mov_b32_e32 v107, v0
	v_mov_b32_e32 v112, v0
	v_mov_b32_e32 v113, v0
	v_mov_b32_e32 v114, v0
	v_mov_b32_e32 v115, v0
	v_mov_b32_e32 v124, v0
	v_mov_b32_e32 v125, v0
	v_mov_b32_e32 v126, v0
	v_mov_b32_e32 v127, v0
	v_mov_b32_e32 v68, v0
	v_mov_b32_e32 v69, v0
	v_mov_b32_e32 v70, v0
	v_mov_b32_e32 v71, v0
	v_mov_b32_e32 v76, v0
	v_mov_b32_e32 v77, v0
	v_mov_b32_e32 v78, v0
	v_mov_b32_e32 v79, v0
	v_mov_b32_e32 v84, v0
	v_mov_b32_e32 v85, v0
	v_mov_b32_e32 v86, v0
	v_mov_b32_e32 v87, v0
	v_mov_b32_e32 v92, v0
	v_mov_b32_e32 v93, v0
	v_mov_b32_e32 v94, v0
	v_mov_b32_e32 v95, v0
	v_mov_b32_e32 v100, v0
	v_mov_b32_e32 v101, v0
	v_mov_b32_e32 v102, v0
	v_mov_b32_e32 v103, v0
	v_mov_b32_e32 v108, v0
	v_mov_b32_e32 v109, v0
	v_mov_b32_e32 v110, v0
	v_mov_b32_e32 v111, v0
	v_mov_b32_e32 v116, v0
	v_mov_b32_e32 v117, v0
	v_mov_b32_e32 v118, v0
	v_mov_b32_e32 v119, v0
	v_mov_b32_e32 v120, v0
	v_mov_b32_e32 v121, v0
	v_mov_b32_e32 v122, v0
	v_mov_b32_e32 v123, v0

.LBB0_350:
	s_andn2_b64 vcc, exec, s[12:13]
	s_cbranch_vccz .Lzskip_2
	v_mov_b32_e32 v127, 0
	v_mov_b32_e32 v126, v127
	v_mov_b32_e32 v125, v127
	v_mov_b32_e32 v124, v127
	v_mov_b32_e32 v123, v127
	v_mov_b32_e32 v122, v127
	v_mov_b32_e32 v121, v127
	v_mov_b32_e32 v120, v127
	v_mov_b32_e32 v111, v127
	v_mov_b32_e32 v110, v127
	v_mov_b32_e32 v109, v127
	v_mov_b32_e32 v108, v127
	v_mov_b32_e32 v107, v127
	v_mov_b32_e32 v106, v127
	v_mov_b32_e32 v105, v127
	v_mov_b32_e32 v104, v127
	v_mov_b32_e32 v95, v127
	v_mov_b32_e32 v94, v127
	v_mov_b32_e32 v93, v127
	v_mov_b32_e32 v92, v127
	v_mov_b32_e32 v91, v127
	v_mov_b32_e32 v90, v127
	v_mov_b32_e32 v89, v127
	v_mov_b32_e32 v88, v127
	v_mov_b32_e32 v79, v127
	v_mov_b32_e32 v78, v127
	v_mov_b32_e32 v77, v127
	v_mov_b32_e32 v76, v127
	v_mov_b32_e32 v75, v127
	v_mov_b32_e32 v74, v127
	v_mov_b32_e32 v73, v127
	v_mov_b32_e32 v72, v127
	v_mov_b32_e32 v119, v127
	v_mov_b32_e32 v118, v127
	v_mov_b32_e32 v117, v127
	v_mov_b32_e32 v116, v127
	v_mov_b32_e32 v115, v127
	v_mov_b32_e32 v114, v127
	v_mov_b32_e32 v113, v127
	v_mov_b32_e32 v112, v127
	v_mov_b32_e32 v103, v127
	v_mov_b32_e32 v102, v127
	v_mov_b32_e32 v101, v127
	v_mov_b32_e32 v100, v127
	v_mov_b32_e32 v99, v127
	v_mov_b32_e32 v98, v127
	v_mov_b32_e32 v97, v127
	v_mov_b32_e32 v96, v127
	v_mov_b32_e32 v87, v127
	v_mov_b32_e32 v86, v127
	v_mov_b32_e32 v85, v127
	v_mov_b32_e32 v84, v127
	v_mov_b32_e32 v83, v127
	v_mov_b32_e32 v82, v127
	v_mov_b32_e32 v81, v127
	v_mov_b32_e32 v80, v127
	v_mov_b32_e32 v71, v127
	v_mov_b32_e32 v70, v127
	v_mov_b32_e32 v69, v127
	v_mov_b32_e32 v68, v127
	v_mov_b32_e32 v67, v127
	v_mov_b32_e32 v66, v127
	v_mov_b32_e32 v65, v127
	v_mov_b32_e32 v64, v127
	v_mov_b32_e32 v63, v127
	v_mov_b32_e32 v62, v127
	v_mov_b32_e32 v61, v127
	v_mov_b32_e32 v60, v127
	v_mov_b32_e32 v59, v127
	v_mov_b32_e32 v58, v127
	v_mov_b32_e32 v57, v127
	v_mov_b32_e32 v56, v127
	v_mov_b32_e32 v47, v127
	v_mov_b32_e32 v46, v127
	v_mov_b32_e32 v45, v127
	v_mov_b32_e32 v44, v127
	v_mov_b32_e32 v43, v127
	v_mov_b32_e32 v42, v127
	v_mov_b32_e32 v41, v127
	v_mov_b32_e32 v40, v127
	v_mov_b32_e32 v31, v127
	v_mov_b32_e32 v30, v127
	v_mov_b32_e32 v29, v127
	v_mov_b32_e32 v28, v127
	v_mov_b32_e32 v27, v127
	v_mov_b32_e32 v26, v127
	v_mov_b32_e32 v25, v127
	v_mov_b32_e32 v24, v127
	v_mov_b32_e32 v15, v127
	v_mov_b32_e32 v14, v127
	v_mov_b32_e32 v13, v127
	v_mov_b32_e32 v12, v127
	v_mov_b32_e32 v11, v127
	v_mov_b32_e32 v10, v127
	v_mov_b32_e32 v9, v127
	v_mov_b32_e32 v8, v127
	v_mov_b32_e32 v55, v127
	v_mov_b32_e32 v54, v127
	v_mov_b32_e32 v53, v127
	v_mov_b32_e32 v52, v127
	v_mov_b32_e32 v51, v127
	v_mov_b32_e32 v50, v127
	v_mov_b32_e32 v49, v127
	v_mov_b32_e32 v48, v127
	v_mov_b32_e32 v39, v127
	v_mov_b32_e32 v38, v127
	v_mov_b32_e32 v37, v127
	v_mov_b32_e32 v36, v127
	v_mov_b32_e32 v35, v127
	v_mov_b32_e32 v34, v127
	v_mov_b32_e32 v33, v127
	v_mov_b32_e32 v32, v127
	v_mov_b32_e32 v23, v127
	v_mov_b32_e32 v22, v127
	v_mov_b32_e32 v21, v127
	v_mov_b32_e32 v20, v127
	v_mov_b32_e32 v19, v127
	v_mov_b32_e32 v18, v127
	v_mov_b32_e32 v17, v127
	v_mov_b32_e32 v16, v127
	v_mov_b32_e32 v7, v127
	v_mov_b32_e32 v6, v127
	v_mov_b32_e32 v5, v127
	v_mov_b32_e32 v4, v127
	v_mov_b32_e32 v3, v127
	v_mov_b32_e32 v2, v127
	v_mov_b32_e32 v1, v127
	v_mov_b32_e32 v0, v127
	s_branch .LBB0_353
.Lzskip_2:
	s_add_u32 s24, s24, 0x80
	s_addc_u32 s25, s25, 0
	s_add_u32 s86, s28, 0x100
	v_mov_b32_e32 v0, 0
	s_addc_u32 s87, s29, 0
	s_mov_b32 s28, 0
	v_mov_b32_e32 v1, v0
	v_mov_b32_e32 v2, v0
	v_mov_b32_e32 v3, v0
	v_mov_b32_e32 v4, v0
	v_mov_b32_e32 v5, v0
	v_mov_b32_e32 v6, v0
	v_mov_b32_e32 v7, v0
	v_mov_b32_e32 v16, v0
	v_mov_b32_e32 v17, v0
	v_mov_b32_e32 v18, v0
	v_mov_b32_e32 v19, v0
	v_mov_b32_e32 v20, v0
	v_mov_b32_e32 v21, v0
	v_mov_b32_e32 v22, v0
	v_mov_b32_e32 v23, v0
	v_mov_b32_e32 v32, v0
	v_mov_b32_e32 v33, v0
	v_mov_b32_e32 v34, v0
	v_mov_b32_e32 v35, v0
	v_mov_b32_e32 v36, v0
	v_mov_b32_e32 v37, v0
	v_mov_b32_e32 v38, v0
	v_mov_b32_e32 v39, v0
	v_mov_b32_e32 v48, v0
	v_mov_b32_e32 v49, v0
	v_mov_b32_e32 v50, v0
	v_mov_b32_e32 v51, v0
	v_mov_b32_e32 v52, v0
	v_mov_b32_e32 v53, v0
	v_mov_b32_e32 v54, v0
	v_mov_b32_e32 v55, v0
	v_mov_b32_e32 v8, v0
	v_mov_b32_e32 v9, v0
	v_mov_b32_e32 v10, v0
	v_mov_b32_e32 v11, v0
	v_mov_b32_e32 v12, v0
	v_mov_b32_e32 v13, v0
	v_mov_b32_e32 v14, v0
	v_mov_b32_e32 v15, v0
	v_mov_b32_e32 v24, v0
	v_mov_b32_e32 v25, v0
	v_mov_b32_e32 v26, v0
	v_mov_b32_e32 v27, v0
	v_mov_b32_e32 v28, v0
	v_mov_b32_e32 v29, v0
	v_mov_b32_e32 v30, v0
	v_mov_b32_e32 v31, v0
	v_mov_b32_e32 v40, v0
	v_mov_b32_e32 v41, v0
	v_mov_b32_e32 v42, v0
	v_mov_b32_e32 v43, v0
	v_mov_b32_e32 v44, v0
	v_mov_b32_e32 v45, v0
	v_mov_b32_e32 v46, v0
	v_mov_b32_e32 v47, v0
	v_mov_b32_e32 v56, v0
	v_mov_b32_e32 v57, v0
	v_mov_b32_e32 v58, v0
	v_mov_b32_e32 v59, v0
	v_mov_b32_e32 v60, v0
	v_mov_b32_e32 v61, v0
	v_mov_b32_e32 v62, v0
	v_mov_b32_e32 v63, v0
	v_mov_b32_e32 v64, v0
	v_mov_b32_e32 v65, v0
	v_mov_b32_e32 v66, v0
	v_mov_b32_e32 v67, v0
	v_mov_b32_e32 v68, v0
	v_mov_b32_e32 v69, v0
	v_mov_b32_e32 v70, v0
	v_mov_b32_e32 v71, v0
	v_mov_b32_e32 v80, v0
	v_mov_b32_e32 v81, v0
	v_mov_b32_e32 v82, v0
	v_mov_b32_e32 v83, v0
	v_mov_b32_e32 v84, v0
	v_mov_b32_e32 v85, v0
	v_mov_b32_e32 v86, v0
	v_mov_b32_e32 v87, v0
	v_mov_b32_e32 v96, v0
	v_mov_b32_e32 v97, v0
	v_mov_b32_e32 v98, v0
	v_mov_b32_e32 v99, v0
	v_mov_b32_e32 v100, v0
	v_mov_b32_e32 v101, v0
	v_mov_b32_e32 v102, v0
	v_mov_b32_e32 v103, v0
	v_mov_b32_e32 v112, v0
	v_mov_b32_e32 v113, v0
	v_mov_b32_e32 v114, v0
	v_mov_b32_e32 v115, v0
	v_mov_b32_e32 v116, v0
	v_mov_b32_e32 v117, v0
	v_mov_b32_e32 v118, v0
	v_mov_b32_e32 v119, v0
	v_mov_b32_e32 v72, v0
	v_mov_b32_e32 v73, v0
	v_mov_b32_e32 v74, v0
	v_mov_b32_e32 v75, v0
	v_mov_b32_e32 v76, v0
	v_mov_b32_e32 v77, v0
	v_mov_b32_e32 v78, v0
	v_mov_b32_e32 v79, v0
	v_mov_b32_e32 v88, v0
	v_mov_b32_e32 v89, v0
	v_mov_b32_e32 v90, v0
	v_mov_b32_e32 v91, v0
	v_mov_b32_e32 v92, v0
	v_mov_b32_e32 v93, v0
	v_mov_b32_e32 v94, v0
	v_mov_b32_e32 v95, v0
	v_mov_b32_e32 v104, v0
	v_mov_b32_e32 v105, v0
	v_mov_b32_e32 v106, v0
	v_mov_b32_e32 v107, v0
	v_mov_b32_e32 v108, v0
	v_mov_b32_e32 v109, v0
	v_mov_b32_e32 v110, v0
	v_mov_b32_e32 v111, v0
	v_mov_b32_e32 v120, v0
	v_mov_b32_e32 v121, v0
	v_mov_b32_e32 v122, v0
	v_mov_b32_e32 v123, v0
	v_mov_b32_e32 v124, v0
	v_mov_b32_e32 v125, v0
	v_mov_b32_e32 v126, v0
	v_mov_b32_e32 v127, v0

.LBB0_569:
	s_andn2_b64 vcc, exec, s[14:15]
	s_waitcnt vmcnt(0)
	s_cbranch_vccz .Lzskip_3
	v_mov_b32_e32 v123, 0
	v_mov_b32_e32 v122, v123
	v_mov_b32_e32 v121, v123
	v_mov_b32_e32 v120, v123
	v_mov_b32_e32 v127, v123
	v_mov_b32_e32 v126, v123
	v_mov_b32_e32 v125, v123
	v_mov_b32_e32 v124, v123
	v_mov_b32_e32 v111, v123
	v_mov_b32_e32 v110, v123
	v_mov_b32_e32 v109, v123
	v_mov_b32_e32 v108, v123
	v_mov_b32_e32 v107, v123
	v_mov_b32_e32 v106, v123
	v_mov_b32_e32 v105, v123
	v_mov_b32_e32 v104, v123
	v_mov_b32_e32 v95, v123
	v_mov_b32_e32 v94, v123
	v_mov_b32_e32 v93, v123
	v_mov_b32_e32 v92, v123
	v_mov_b32_e32 v91, v123
	v_mov_b32_e32 v90, v123
	v_mov_b32_e32 v89, v123
	v_mov_b32_e32 v88, v123
	v_mov_b32_e32 v79, v123
	v_mov_b32_e32 v78, v123
	v_mov_b32_e32 v77, v123
	v_mov_b32_e32 v76, v123
	v_mov_b32_e32 v75, v123
	v_mov_b32_e32 v74, v123
	v_mov_b32_e32 v73, v123
	v_mov_b32_e32 v72, v123
	v_mov_b32_e32 v119, v123
	v_mov_b32_e32 v118, v123
	v_mov_b32_e32 v117, v123
	v_mov_b32_e32 v116, v123
	v_mov_b32_e32 v115, v123
	v_mov_b32_e32 v114, v123
	v_mov_b32_e32 v113, v123
	v_mov_b32_e32 v112, v123
	v_mov_b32_e32 v103, v123
	v_mov_b32_e32 v102, v123
	v_mov_b32_e32 v101, v123
	v_mov_b32_e32 v100, v123
	v_mov_b32_e32 v99, v123
	v_mov_b32_e32 v98, v123
	v_mov_b32_e32 v97, v123
	v_mov_b32_e32 v96, v123
	v_mov_b32_e32 v87, v123
	v_mov_b32_e32 v86, v123
	v_mov_b32_e32 v85, v123
	v_mov_b32_e32 v84, v123
	v_mov_b32_e32 v83, v123
	v_mov_b32_e32 v82, v123
	v_mov_b32_e32 v81, v123
	v_mov_b32_e32 v80, v123
	v_mov_b32_e32 v71, v123
	v_mov_b32_e32 v70, v123
	v_mov_b32_e32 v69, v123
	v_mov_b32_e32 v68, v123
	v_mov_b32_e32 v67, v123
	v_mov_b32_e32 v66, v123
	v_mov_b32_e32 v65, v123
	v_mov_b32_e32 v64, v123
	v_mov_b32_e32 v63, v123
	v_mov_b32_e32 v62, v123
	v_mov_b32_e32 v61, v123
	v_mov_b32_e32 v60, v123
	v_mov_b32_e32 v59, v123
	v_mov_b32_e32 v58, v123
	v_mov_b32_e32 v57, v123
	v_mov_b32_e32 v56, v123
	v_mov_b32_e32 v47, v123
	v_mov_b32_e32 v46, v123
	v_mov_b32_e32 v45, v123
	v_mov_b32_e32 v44, v123
	v_mov_b32_e32 v43, v123
	v_mov_b32_e32 v42, v123
	v_mov_b32_e32 v41, v123
	v_mov_b32_e32 v40, v123
	v_mov_b32_e32 v31, v123
	v_mov_b32_e32 v30, v123
	v_mov_b32_e32 v29, v123
	v_mov_b32_e32 v28, v123
	v_mov_b32_e32 v27, v123
	v_mov_b32_e32 v26, v123
	v_mov_b32_e32 v25, v123
	v_mov_b32_e32 v24, v123
	v_mov_b32_e32 v15, v123
	v_mov_b32_e32 v14, v123
	v_mov_b32_e32 v13, v123
	v_mov_b32_e32 v12, v123
	v_mov_b32_e32 v11, v123
	v_mov_b32_e32 v10, v123
	v_mov_b32_e32 v9, v123
	v_mov_b32_e32 v8, v123
	v_mov_b32_e32 v55, v123
	v_mov_b32_e32 v54, v123
	v_mov_b32_e32 v53, v123
	v_mov_b32_e32 v52, v123
	v_mov_b32_e32 v51, v123
	v_mov_b32_e32 v50, v123
	v_mov_b32_e32 v49, v123
	v_mov_b32_e32 v48, v123
	v_mov_b32_e32 v39, v123
	v_mov_b32_e32 v38, v123
	v_mov_b32_e32 v37, v123
	v_mov_b32_e32 v36, v123
	v_mov_b32_e32 v35, v123
	v_mov_b32_e32 v34, v123
	v_mov_b32_e32 v33, v123
	v_mov_b32_e32 v32, v123
	v_mov_b32_e32 v23, v123
	v_mov_b32_e32 v22, v123
	v_mov_b32_e32 v21, v123
	v_mov_b32_e32 v20, v123
	v_mov_b32_e32 v19, v123
	v_mov_b32_e32 v18, v123
	v_mov_b32_e32 v17, v123
	v_mov_b32_e32 v16, v123
	v_mov_b32_e32 v7, v123
	v_mov_b32_e32 v6, v123
	v_mov_b32_e32 v5, v123
	v_mov_b32_e32 v4, v123
	v_mov_b32_e32 v3, v123
	v_mov_b32_e32 v2, v123
	v_mov_b32_e32 v1, v123
	v_mov_b32_e32 v0, v123
	s_branch .LBB0_573
.Lzskip_3:
	s_add_u32 s24, s24, 0x80
	s_addc_u32 s25, s25, 0
	s_add_u32 s68, s28, 0x100
	v_mov_b32_e32 v0, 0
	s_addc_u32 s69, s29, 0
	s_mov_b32 s28, 0
	v_mov_b32_e32 v1, v0
	v_mov_b32_e32 v2, v0
	v_mov_b32_e32 v3, v0
	v_mov_b32_e32 v4, v0
	v_mov_b32_e32 v5, v0
	v_mov_b32_e32 v6, v0
	v_mov_b32_e32 v7, v0
	v_mov_b32_e32 v16, v0
	v_mov_b32_e32 v17, v0
	v_mov_b32_e32 v18, v0
	v_mov_b32_e32 v19, v0
	v_mov_b32_e32 v20, v0
	v_mov_b32_e32 v21, v0
	v_mov_b32_e32 v22, v0
	v_mov_b32_e32 v23, v0
	v_mov_b32_e32 v32, v0
	v_mov_b32_e32 v33, v0
	v_mov_b32_e32 v34, v0
	v_mov_b32_e32 v35, v0
	v_mov_b32_e32 v36, v0
	v_mov_b32_e32 v37, v0
	v_mov_b32_e32 v38, v0
	v_mov_b32_e32 v39, v0
	v_mov_b32_e32 v48, v0
	v_mov_b32_e32 v49, v0
	v_mov_b32_e32 v50, v0
	v_mov_b32_e32 v51, v0
	v_mov_b32_e32 v52, v0
	v_mov_b32_e32 v53, v0
	v_mov_b32_e32 v54, v0
	v_mov_b32_e32 v55, v0
	v_mov_b32_e32 v8, v0
	v_mov_b32_e32 v9, v0
	v_mov_b32_e32 v10, v0
	v_mov_b32_e32 v11, v0
	v_mov_b32_e32 v12, v0
	v_mov_b32_e32 v13, v0
	v_mov_b32_e32 v14, v0
	v_mov_b32_e32 v15, v0
	v_mov_b32_e32 v24, v0
	v_mov_b32_e32 v25, v0
	v_mov_b32_e32 v26, v0
	v_mov_b32_e32 v27, v0
	v_mov_b32_e32 v28, v0
	v_mov_b32_e32 v29, v0
	v_mov_b32_e32 v30, v0
	v_mov_b32_e32 v31, v0
	v_mov_b32_e32 v40, v0
	v_mov_b32_e32 v41, v0
	v_mov_b32_e32 v42, v0
	v_mov_b32_e32 v43, v0
	v_mov_b32_e32 v44, v0
	v_mov_b32_e32 v45, v0
	v_mov_b32_e32 v46, v0
	v_mov_b32_e32 v47, v0
	v_mov_b32_e32 v56, v0
	v_mov_b32_e32 v57, v0
	v_mov_b32_e32 v58, v0
	v_mov_b32_e32 v59, v0
	v_mov_b32_e32 v60, v0
	v_mov_b32_e32 v61, v0
	v_mov_b32_e32 v62, v0
	v_mov_b32_e32 v63, v0
	v_mov_b32_e32 v64, v0
	v_mov_b32_e32 v65, v0
	v_mov_b32_e32 v66, v0
	v_mov_b32_e32 v67, v0
	v_mov_b32_e32 v68, v0
	v_mov_b32_e32 v69, v0
	v_mov_b32_e32 v70, v0
	v_mov_b32_e32 v71, v0
	v_mov_b32_e32 v80, v0
	v_mov_b32_e32 v81, v0
	v_mov_b32_e32 v82, v0
	v_mov_b32_e32 v83, v0
	v_mov_b32_e32 v84, v0
	v_mov_b32_e32 v85, v0
	v_mov_b32_e32 v86, v0
	v_mov_b32_e32 v87, v0
	v_mov_b32_e32 v96, v0
	v_mov_b32_e32 v97, v0
	v_mov_b32_e32 v98, v0
	v_mov_b32_e32 v99, v0
	v_mov_b32_e32 v100, v0
	v_mov_b32_e32 v101, v0
	v_mov_b32_e32 v102, v0
	v_mov_b32_e32 v103, v0
	v_mov_b32_e32 v112, v0
	v_mov_b32_e32 v113, v0
	v_mov_b32_e32 v114, v0
	v_mov_b32_e32 v115, v0
	v_mov_b32_e32 v116, v0
	v_mov_b32_e32 v117, v0
	v_mov_b32_e32 v118, v0
	v_mov_b32_e32 v119, v0
	v_mov_b32_e32 v72, v0
	v_mov_b32_e32 v73, v0
	v_mov_b32_e32 v74, v0
	v_mov_b32_e32 v75, v0
	v_mov_b32_e32 v76, v0
	v_mov_b32_e32 v77, v0
	v_mov_b32_e32 v78, v0
	v_mov_b32_e32 v79, v0
	v_mov_b32_e32 v88, v0
	v_mov_b32_e32 v89, v0
	v_mov_b32_e32 v90, v0
	v_mov_b32_e32 v91, v0
	v_mov_b32_e32 v92, v0
	v_mov_b32_e32 v93, v0
	v_mov_b32_e32 v94, v0
	v_mov_b32_e32 v95, v0
	v_mov_b32_e32 v104, v0
	v_mov_b32_e32 v105, v0
	v_mov_b32_e32 v106, v0
	v_mov_b32_e32 v107, v0
	v_mov_b32_e32 v108, v0
	v_mov_b32_e32 v109, v0
	v_mov_b32_e32 v110, v0
	v_mov_b32_e32 v111, v0
	v_mov_b32_e32 v124, v0
	v_mov_b32_e32 v125, v0
	v_mov_b32_e32 v126, v0
	v_mov_b32_e32 v127, v0
	v_mov_b32_e32 v120, v0
	v_mov_b32_e32 v121, v0
	v_mov_b32_e32 v122, v0
	v_mov_b32_e32 v123, v0

.LBB0_595:
	s_andn2_b64 vcc, exec, s[14:15]
	s_waitcnt vmcnt(0)
	s_cbranch_vccz .Lzskip_4
	v_mov_b32_e32 v147, 0
	v_mov_b32_e32 v146, v147
	v_mov_b32_e32 v145, v147
	v_mov_b32_e32 v144, v147
	v_mov_b32_e32 v135, v147
	v_mov_b32_e32 v134, v147
	v_mov_b32_e32 v133, v147
	v_mov_b32_e32 v132, v147
	v_mov_b32_e32 v111, v147
	v_mov_b32_e32 v110, v147
	v_mov_b32_e32 v109, v147
	v_mov_b32_e32 v108, v147
	v_mov_b32_e32 v107, v147
	v_mov_b32_e32 v106, v147
	v_mov_b32_e32 v105, v147
	v_mov_b32_e32 v104, v147
	v_mov_b32_e32 v95, v147
	v_mov_b32_e32 v94, v147
	v_mov_b32_e32 v93, v147
	v_mov_b32_e32 v92, v147
	v_mov_b32_e32 v91, v147
	v_mov_b32_e32 v90, v147
	v_mov_b32_e32 v89, v147
	v_mov_b32_e32 v88, v147
	v_mov_b32_e32 v79, v147
	v_mov_b32_e32 v78, v147
	v_mov_b32_e32 v77, v147
	v_mov_b32_e32 v76, v147
	v_mov_b32_e32 v75, v147
	v_mov_b32_e32 v74, v147
	v_mov_b32_e32 v73, v147
	v_mov_b32_e32 v72, v147
	v_mov_b32_e32 v127, v147
	v_mov_b32_e32 v126, v147
	v_mov_b32_e32 v125, v147
	v_mov_b32_e32 v124, v147
	v_mov_b32_e32 v119, v147
	v_mov_b32_e32 v118, v147
	v_mov_b32_e32 v117, v147
	v_mov_b32_e32 v116, v147
	v_mov_b32_e32 v103, v147
	v_mov_b32_e32 v102, v147
	v_mov_b32_e32 v101, v147
	v_mov_b32_e32 v100, v147
	v_mov_b32_e32 v99, v147
	v_mov_b32_e32 v98, v147
	v_mov_b32_e32 v97, v147
	v_mov_b32_e32 v96, v147
	v_mov_b32_e32 v87, v147
	v_mov_b32_e32 v86, v147
	v_mov_b32_e32 v85, v147
	v_mov_b32_e32 v84, v147
	v_mov_b32_e32 v83, v147
	v_mov_b32_e32 v82, v147
	v_mov_b32_e32 v81, v147
	v_mov_b32_e32 v80, v147
	v_mov_b32_e32 v71, v147
	v_mov_b32_e32 v70, v147
	v_mov_b32_e32 v69, v147
	v_mov_b32_e32 v68, v147
	v_mov_b32_e32 v67, v147
	v_mov_b32_e32 v66, v147
	v_mov_b32_e32 v65, v147
	v_mov_b32_e32 v64, v147
	v_mov_b32_e32 v63, v147
	v_mov_b32_e32 v62, v147
	v_mov_b32_e32 v61, v147
	v_mov_b32_e32 v60, v147
	v_mov_b32_e32 v59, v147
	v_mov_b32_e32 v58, v147
	v_mov_b32_e32 v57, v147
	v_mov_b32_e32 v56, v147
	v_mov_b32_e32 v47, v147
	v_mov_b32_e32 v46, v147
	v_mov_b32_e32 v45, v147
	v_mov_b32_e32 v44, v147
	v_mov_b32_e32 v43, v147
	v_mov_b32_e32 v42, v147
	v_mov_b32_e32 v41, v147
	v_mov_b32_e32 v40, v147
	v_mov_b32_e32 v31, v147
	v_mov_b32_e32 v30, v147
	v_mov_b32_e32 v29, v147
	v_mov_b32_e32 v28, v147
	v_mov_b32_e32 v27, v147
	v_mov_b32_e32 v26, v147
	v_mov_b32_e32 v25, v147
	v_mov_b32_e32 v24, v147
	v_mov_b32_e32 v15, v147
	v_mov_b32_e32 v14, v147
	v_mov_b32_e32 v13, v147
	v_mov_b32_e32 v12, v147
	v_mov_b32_e32 v11, v147
	v_mov_b32_e32 v10, v147
	v_mov_b32_e32 v9, v147
	v_mov_b32_e32 v8, v147
	v_mov_b32_e32 v55, v147
	v_mov_b32_e32 v54, v147
	v_mov_b32_e32 v53, v147
	v_mov_b32_e32 v52, v147
	v_mov_b32_e32 v51, v147
	v_mov_b32_e32 v50, v147
	v_mov_b32_e32 v49, v147
	v_mov_b32_e32 v48, v147
	v_mov_b32_e32 v39, v147
	v_mov_b32_e32 v38, v147
	v_mov_b32_e32 v37, v147
	v_mov_b32_e32 v36, v147
	v_mov_b32_e32 v35, v147
	v_mov_b32_e32 v34, v147
	v_mov_b32_e32 v33, v147
	v_mov_b32_e32 v32, v147
	v_mov_b32_e32 v23, v147
	v_mov_b32_e32 v22, v147
	v_mov_b32_e32 v21, v147
	v_mov_b32_e32 v20, v147
	v_mov_b32_e32 v19, v147
	v_mov_b32_e32 v18, v147
	v_mov_b32_e32 v17, v147
	v_mov_b32_e32 v16, v147
	v_mov_b32_e32 v7, v147
	v_mov_b32_e32 v6, v147
	v_mov_b32_e32 v5, v147
	v_mov_b32_e32 v4, v147
	v_mov_b32_e32 v3, v147
	v_mov_b32_e32 v2, v147
	v_mov_b32_e32 v1, v147
	v_mov_b32_e32 v0, v147
	s_branch .LBB0_598
.Lzskip_4:
	s_add_u32 s24, s24, 0x80
	s_addc_u32 s25, s25, 0
	s_add_u32 s16, s28, 0x100
	v_mov_b32_e32 v0, 0
	s_addc_u32 s20, s29, 0
	s_mov_b32 s26, 0
	v_mov_b32_e32 v1, v0
	v_mov_b32_e32 v2, v0
	v_mov_b32_e32 v3, v0
	v_mov_b32_e32 v4, v0
	v_mov_b32_e32 v5, v0
	v_mov_b32_e32 v6, v0
	v_mov_b32_e32 v7, v0
	v_mov_b32_e32 v16, v0
	v_mov_b32_e32 v17, v0
	v_mov_b32_e32 v18, v0
	v_mov_b32_e32 v19, v0
	v_mov_b32_e32 v20, v0
	v_mov_b32_e32 v21, v0
	v_mov_b32_e32 v22, v0
	v_mov_b32_e32 v23, v0
	v_mov_b32_e32 v32, v0
	v_mov_b32_e32 v33, v0
	v_mov_b32_e32 v34, v0
	v_mov_b32_e32 v35, v0
	v_mov_b32_e32 v36, v0
	v_mov_b32_e32 v37, v0
	v_mov_b32_e32 v38, v0
	v_mov_b32_e32 v39, v0
	v_mov_b32_e32 v48, v0
	v_mov_b32_e32 v49, v0
	v_mov_b32_e32 v50, v0
	v_mov_b32_e32 v51, v0
	v_mov_b32_e32 v52, v0
	v_mov_b32_e32 v53, v0
	v_mov_b32_e32 v54, v0
	v_mov_b32_e32 v55, v0
	v_mov_b32_e32 v8, v0
	v_mov_b32_e32 v9, v0
	v_mov_b32_e32 v10, v0
	v_mov_b32_e32 v11, v0
	v_mov_b32_e32 v12, v0
	v_mov_b32_e32 v13, v0
	v_mov_b32_e32 v14, v0
	v_mov_b32_e32 v15, v0
	v_mov_b32_e32 v24, v0
	v_mov_b32_e32 v25, v0
	v_mov_b32_e32 v26, v0
	v_mov_b32_e32 v27, v0
	v_mov_b32_e32 v28, v0
	v_mov_b32_e32 v29, v0
	v_mov_b32_e32 v30, v0
	v_mov_b32_e32 v31, v0
	v_mov_b32_e32 v40, v0
	v_mov_b32_e32 v41, v0
	v_mov_b32_e32 v42, v0
	v_mov_b32_e32 v43, v0
	v_mov_b32_e32 v44, v0
	v_mov_b32_e32 v45, v0
	v_mov_b32_e32 v46, v0
	v_mov_b32_e32 v47, v0
	v_mov_b32_e32 v56, v0
	v_mov_b32_e32 v57, v0
	v_mov_b32_e32 v58, v0
	v_mov_b32_e32 v59, v0
	v_mov_b32_e32 v60, v0
	v_mov_b32_e32 v61, v0
	v_mov_b32_e32 v62, v0
	v_mov_b32_e32 v63, v0
	v_mov_b32_e32 v64, v0
	v_mov_b32_e32 v65, v0
	v_mov_b32_e32 v66, v0
	v_mov_b32_e32 v67, v0
	v_mov_b32_e32 v68, v0
	v_mov_b32_e32 v69, v0
	v_mov_b32_e32 v70, v0
	v_mov_b32_e32 v71, v0
	v_mov_b32_e32 v80, v0
	v_mov_b32_e32 v81, v0
	v_mov_b32_e32 v82, v0
	v_mov_b32_e32 v83, v0
	v_mov_b32_e32 v84, v0
	v_mov_b32_e32 v85, v0
	v_mov_b32_e32 v86, v0
	v_mov_b32_e32 v87, v0
	v_mov_b32_e32 v96, v0
	v_mov_b32_e32 v97, v0
	v_mov_b32_e32 v98, v0
	v_mov_b32_e32 v99, v0
	v_mov_b32_e32 v100, v0
	v_mov_b32_e32 v101, v0
	v_mov_b32_e32 v102, v0
	v_mov_b32_e32 v103, v0
	v_mov_b32_e32 v116, v0
	v_mov_b32_e32 v117, v0
	v_mov_b32_e32 v118, v0
	v_mov_b32_e32 v119, v0
	v_mov_b32_e32 v124, v0
	v_mov_b32_e32 v125, v0
	v_mov_b32_e32 v126, v0
	v_mov_b32_e32 v127, v0
	v_mov_b32_e32 v72, v0
	v_mov_b32_e32 v73, v0
	v_mov_b32_e32 v74, v0
	v_mov_b32_e32 v75, v0
	v_mov_b32_e32 v76, v0
	v_mov_b32_e32 v77, v0
	v_mov_b32_e32 v78, v0
	v_mov_b32_e32 v79, v0
	v_mov_b32_e32 v88, v0
	v_mov_b32_e32 v89, v0
	v_mov_b32_e32 v90, v0
	v_mov_b32_e32 v91, v0
	v_mov_b32_e32 v92, v0
	v_mov_b32_e32 v93, v0
	v_mov_b32_e32 v94, v0
	v_mov_b32_e32 v95, v0
	v_mov_b32_e32 v104, v0
	v_mov_b32_e32 v105, v0
	v_mov_b32_e32 v106, v0
	v_mov_b32_e32 v107, v0
	v_mov_b32_e32 v108, v0
	v_mov_b32_e32 v109, v0
	v_mov_b32_e32 v110, v0
	v_mov_b32_e32 v111, v0
	v_mov_b32_e32 v132, v0
	v_mov_b32_e32 v133, v0
	v_mov_b32_e32 v134, v0
	v_mov_b32_e32 v135, v0
	v_mov_b32_e32 v144, v0
	v_mov_b32_e32 v145, v0
	v_mov_b32_e32 v146, v0
	v_mov_b32_e32 v147, v0

.LBB0_678:
	s_andn2_b64 vcc, exec, s[18:19]
	s_waitcnt lgkmcnt(0)
	s_cbranch_vccz .Lzskip_5
	v_mov_b32_e32 v123, 0
	v_mov_b32_e32 v122, v123
	v_mov_b32_e32 v121, v123
	v_mov_b32_e32 v120, v123
	v_mov_b32_e32 v127, v123
	v_mov_b32_e32 v126, v123
	v_mov_b32_e32 v125, v123
	v_mov_b32_e32 v124, v123
	v_mov_b32_e32 v111, v123
	v_mov_b32_e32 v110, v123
	v_mov_b32_e32 v109, v123
	v_mov_b32_e32 v108, v123
	v_mov_b32_e32 v107, v123
	v_mov_b32_e32 v106, v123
	v_mov_b32_e32 v105, v123
	v_mov_b32_e32 v104, v123
	v_mov_b32_e32 v95, v123
	v_mov_b32_e32 v94, v123
	v_mov_b32_e32 v93, v123
	v_mov_b32_e32 v92, v123
	v_mov_b32_e32 v91, v123
	v_mov_b32_e32 v90, v123
	v_mov_b32_e32 v89, v123
	v_mov_b32_e32 v88, v123
	v_mov_b32_e32 v79, v123
	v_mov_b32_e32 v78, v123
	v_mov_b32_e32 v77, v123
	v_mov_b32_e32 v76, v123
	v_mov_b32_e32 v75, v123
	v_mov_b32_e32 v74, v123
	v_mov_b32_e32 v73, v123
	v_mov_b32_e32 v72, v123
	v_mov_b32_e32 v119, v123
	v_mov_b32_e32 v118, v123
	v_mov_b32_e32 v117, v123
	v_mov_b32_e32 v116, v123
	v_mov_b32_e32 v115, v123
	v_mov_b32_e32 v114, v123
	v_mov_b32_e32 v113, v123
	v_mov_b32_e32 v112, v123
	v_mov_b32_e32 v103, v123
	v_mov_b32_e32 v102, v123
	v_mov_b32_e32 v101, v123
	v_mov_b32_e32 v100, v123
	v_mov_b32_e32 v99, v123
	v_mov_b32_e32 v98, v123
	v_mov_b32_e32 v97, v123
	v_mov_b32_e32 v96, v123
	v_mov_b32_e32 v87, v123
	v_mov_b32_e32 v86, v123
	v_mov_b32_e32 v85, v123
	v_mov_b32_e32 v84, v123
	v_mov_b32_e32 v83, v123
	v_mov_b32_e32 v82, v123
	v_mov_b32_e32 v81, v123
	v_mov_b32_e32 v80, v123
	v_mov_b32_e32 v71, v123
	v_mov_b32_e32 v70, v123
	v_mov_b32_e32 v69, v123
	v_mov_b32_e32 v68, v123
	v_mov_b32_e32 v67, v123
	v_mov_b32_e32 v66, v123
	v_mov_b32_e32 v65, v123
	v_mov_b32_e32 v64, v123
	v_mov_b32_e32 v63, v123
	v_mov_b32_e32 v62, v123
	v_mov_b32_e32 v61, v123
	v_mov_b32_e32 v60, v123
	v_mov_b32_e32 v59, v123
	v_mov_b32_e32 v58, v123
	v_mov_b32_e32 v57, v123
	v_mov_b32_e32 v56, v123
	v_mov_b32_e32 v47, v123
	v_mov_b32_e32 v46, v123
	v_mov_b32_e32 v45, v123
	v_mov_b32_e32 v44, v123
	v_mov_b32_e32 v43, v123
	v_mov_b32_e32 v42, v123
	v_mov_b32_e32 v41, v123
	v_mov_b32_e32 v40, v123
	v_mov_b32_e32 v31, v123
	v_mov_b32_e32 v30, v123
	v_mov_b32_e32 v29, v123
	v_mov_b32_e32 v28, v123
	v_mov_b32_e32 v27, v123
	v_mov_b32_e32 v26, v123
	v_mov_b32_e32 v25, v123
	v_mov_b32_e32 v24, v123
	v_mov_b32_e32 v15, v123
	v_mov_b32_e32 v14, v123
	v_mov_b32_e32 v13, v123
	v_mov_b32_e32 v12, v123
	v_mov_b32_e32 v11, v123
	v_mov_b32_e32 v10, v123
	v_mov_b32_e32 v9, v123
	v_mov_b32_e32 v8, v123
	v_mov_b32_e32 v55, v123
	v_mov_b32_e32 v54, v123
	v_mov_b32_e32 v53, v123
	v_mov_b32_e32 v52, v123
	v_mov_b32_e32 v51, v123
	v_mov_b32_e32 v50, v123
	v_mov_b32_e32 v49, v123
	v_mov_b32_e32 v48, v123
	v_mov_b32_e32 v39, v123
	v_mov_b32_e32 v38, v123
	v_mov_b32_e32 v37, v123
	v_mov_b32_e32 v36, v123
	v_mov_b32_e32 v35, v123
	v_mov_b32_e32 v34, v123
	v_mov_b32_e32 v33, v123
	v_mov_b32_e32 v32, v123
	v_mov_b32_e32 v23, v123
	v_mov_b32_e32 v22, v123
	v_mov_b32_e32 v21, v123
	v_mov_b32_e32 v20, v123
	v_mov_b32_e32 v19, v123
	v_mov_b32_e32 v18, v123
	v_mov_b32_e32 v17, v123
	v_mov_b32_e32 v16, v123
	v_mov_b32_e32 v7, v123
	v_mov_b32_e32 v6, v123
	v_mov_b32_e32 v5, v123
	v_mov_b32_e32 v4, v123
	v_mov_b32_e32 v3, v123
	v_mov_b32_e32 v2, v123
	v_mov_b32_e32 v1, v123
	v_mov_b32_e32 v0, v123
	s_branch .LBB0_682
.Lzskip_5:
	s_add_u32 s24, s24, 0x80
	s_addc_u32 s25, s25, 0
	s_add_u32 s73, s28, 0x100
	v_mov_b32_e32 v0, 0
	s_addc_u32 s82, s29, 0
	s_mov_b32 s28, 0
	v_mov_b32_e32 v1, v0
	v_mov_b32_e32 v2, v0
	v_mov_b32_e32 v3, v0
	v_mov_b32_e32 v4, v0
	v_mov_b32_e32 v5, v0
	v_mov_b32_e32 v6, v0
	v_mov_b32_e32 v7, v0
	v_mov_b32_e32 v16, v0
	v_mov_b32_e32 v17, v0
	v_mov_b32_e32 v18, v0
	v_mov_b32_e32 v19, v0
	v_mov_b32_e32 v20, v0
	v_mov_b32_e32 v21, v0
	v_mov_b32_e32 v22, v0
	v_mov_b32_e32 v23, v0
	v_mov_b32_e32 v32, v0
	v_mov_b32_e32 v33, v0
	v_mov_b32_e32 v34, v0
	v_mov_b32_e32 v35, v0
	v_mov_b32_e32 v36, v0
	v_mov_b32_e32 v37, v0
	v_mov_b32_e32 v38, v0
	v_mov_b32_e32 v39, v0
	v_mov_b32_e32 v48, v0
	v_mov_b32_e32 v49, v0
	v_mov_b32_e32 v50, v0
	v_mov_b32_e32 v51, v0
	v_mov_b32_e32 v52, v0
	v_mov_b32_e32 v53, v0
	v_mov_b32_e32 v54, v0
	v_mov_b32_e32 v55, v0
	v_mov_b32_e32 v8, v0
	v_mov_b32_e32 v9, v0
	v_mov_b32_e32 v10, v0
	v_mov_b32_e32 v11, v0
	v_mov_b32_e32 v12, v0
	v_mov_b32_e32 v13, v0
	v_mov_b32_e32 v14, v0
	v_mov_b32_e32 v15, v0
	v_mov_b32_e32 v24, v0
	v_mov_b32_e32 v25, v0
	v_mov_b32_e32 v26, v0
	v_mov_b32_e32 v27, v0
	v_mov_b32_e32 v28, v0
	v_mov_b32_e32 v29, v0
	v_mov_b32_e32 v30, v0
	v_mov_b32_e32 v31, v0
	v_mov_b32_e32 v40, v0
	v_mov_b32_e32 v41, v0
	v_mov_b32_e32 v42, v0
	v_mov_b32_e32 v43, v0
	v_mov_b32_e32 v44, v0
	v_mov_b32_e32 v45, v0
	v_mov_b32_e32 v46, v0
	v_mov_b32_e32 v47, v0
	v_mov_b32_e32 v56, v0
	v_mov_b32_e32 v57, v0
	v_mov_b32_e32 v58, v0
	v_mov_b32_e32 v59, v0
	v_mov_b32_e32 v60, v0
	v_mov_b32_e32 v61, v0
	v_mov_b32_e32 v62, v0
	v_mov_b32_e32 v63, v0
	v_mov_b32_e32 v64, v0
	v_mov_b32_e32 v65, v0
	v_mov_b32_e32 v66, v0
	v_mov_b32_e32 v67, v0
	v_mov_b32_e32 v68, v0
	v_mov_b32_e32 v69, v0
	v_mov_b32_e32 v70, v0
	v_mov_b32_e32 v71, v0
	v_mov_b32_e32 v80, v0
	v_mov_b32_e32 v81, v0
	v_mov_b32_e32 v82, v0
	v_mov_b32_e32 v83, v0
	v_mov_b32_e32 v84, v0
	v_mov_b32_e32 v85, v0
	v_mov_b32_e32 v86, v0
	v_mov_b32_e32 v87, v0
	v_mov_b32_e32 v96, v0
	v_mov_b32_e32 v97, v0
	v_mov_b32_e32 v98, v0
	v_mov_b32_e32 v99, v0
	v_mov_b32_e32 v100, v0
	v_mov_b32_e32 v101, v0
	v_mov_b32_e32 v102, v0
	v_mov_b32_e32 v103, v0
	v_mov_b32_e32 v112, v0
	v_mov_b32_e32 v113, v0
	v_mov_b32_e32 v114, v0
	v_mov_b32_e32 v115, v0
	v_mov_b32_e32 v116, v0
	v_mov_b32_e32 v117, v0
	v_mov_b32_e32 v118, v0
	v_mov_b32_e32 v119, v0
	v_mov_b32_e32 v72, v0
	v_mov_b32_e32 v73, v0
	v_mov_b32_e32 v74, v0
	v_mov_b32_e32 v75, v0
	v_mov_b32_e32 v76, v0
	v_mov_b32_e32 v77, v0
	v_mov_b32_e32 v78, v0
	v_mov_b32_e32 v79, v0
	v_mov_b32_e32 v88, v0
	v_mov_b32_e32 v89, v0
	v_mov_b32_e32 v90, v0
	v_mov_b32_e32 v91, v0
	v_mov_b32_e32 v92, v0
	v_mov_b32_e32 v93, v0
	v_mov_b32_e32 v94, v0
	v_mov_b32_e32 v95, v0
	v_mov_b32_e32 v104, v0
	v_mov_b32_e32 v105, v0
	v_mov_b32_e32 v106, v0
	v_mov_b32_e32 v107, v0
	v_mov_b32_e32 v108, v0
	v_mov_b32_e32 v109, v0
	v_mov_b32_e32 v110, v0
	v_mov_b32_e32 v111, v0
	v_mov_b32_e32 v124, v0
	v_mov_b32_e32 v125, v0
	v_mov_b32_e32 v126, v0
	v_mov_b32_e32 v127, v0
	v_mov_b32_e32 v120, v0
	v_mov_b32_e32 v121, v0
	v_mov_b32_e32 v122, v0
	v_mov_b32_e32 v123, v0

.LBB0_780:
	s_andn2_b64 vcc, exec, s[18:19]
	s_waitcnt vmcnt(0)
	s_cbranch_vccz .Lzskip_6
	v_mov_b32_e32 v127, 0
	v_mov_b32_e32 v126, v127
	v_mov_b32_e32 v125, v127
	v_mov_b32_e32 v124, v127
	v_mov_b32_e32 v123, v127
	v_mov_b32_e32 v122, v127
	v_mov_b32_e32 v121, v127
	v_mov_b32_e32 v120, v127
	v_mov_b32_e32 v111, v127
	v_mov_b32_e32 v110, v127
	v_mov_b32_e32 v109, v127
	v_mov_b32_e32 v108, v127
	v_mov_b32_e32 v107, v127
	v_mov_b32_e32 v106, v127
	v_mov_b32_e32 v105, v127
	v_mov_b32_e32 v104, v127
	v_mov_b32_e32 v95, v127
	v_mov_b32_e32 v94, v127
	v_mov_b32_e32 v93, v127
	v_mov_b32_e32 v92, v127
	v_mov_b32_e32 v91, v127
	v_mov_b32_e32 v90, v127
	v_mov_b32_e32 v89, v127
	v_mov_b32_e32 v88, v127
	v_mov_b32_e32 v79, v127
	v_mov_b32_e32 v78, v127
	v_mov_b32_e32 v77, v127
	v_mov_b32_e32 v76, v127
	v_mov_b32_e32 v75, v127
	v_mov_b32_e32 v74, v127
	v_mov_b32_e32 v73, v127
	v_mov_b32_e32 v72, v127
	v_mov_b32_e32 v119, v127
	v_mov_b32_e32 v118, v127
	v_mov_b32_e32 v117, v127
	v_mov_b32_e32 v116, v127
	v_mov_b32_e32 v115, v127
	v_mov_b32_e32 v114, v127
	v_mov_b32_e32 v113, v127
	v_mov_b32_e32 v112, v127
	v_mov_b32_e32 v103, v127
	v_mov_b32_e32 v102, v127
	v_mov_b32_e32 v101, v127
	v_mov_b32_e32 v100, v127
	v_mov_b32_e32 v99, v127
	v_mov_b32_e32 v98, v127
	v_mov_b32_e32 v97, v127
	v_mov_b32_e32 v96, v127
	v_mov_b32_e32 v87, v127
	v_mov_b32_e32 v86, v127
	v_mov_b32_e32 v85, v127
	v_mov_b32_e32 v84, v127
	v_mov_b32_e32 v83, v127
	v_mov_b32_e32 v82, v127
	v_mov_b32_e32 v81, v127
	v_mov_b32_e32 v80, v127
	v_mov_b32_e32 v71, v127
	v_mov_b32_e32 v70, v127
	v_mov_b32_e32 v69, v127
	v_mov_b32_e32 v68, v127
	v_mov_b32_e32 v67, v127
	v_mov_b32_e32 v66, v127
	v_mov_b32_e32 v65, v127
	v_mov_b32_e32 v64, v127
	v_mov_b32_e32 v63, v127
	v_mov_b32_e32 v62, v127
	v_mov_b32_e32 v61, v127
	v_mov_b32_e32 v60, v127
	v_mov_b32_e32 v59, v127
	v_mov_b32_e32 v58, v127
	v_mov_b32_e32 v57, v127
	v_mov_b32_e32 v56, v127
	v_mov_b32_e32 v47, v127
	v_mov_b32_e32 v46, v127
	v_mov_b32_e32 v45, v127
	v_mov_b32_e32 v44, v127
	v_mov_b32_e32 v43, v127
	v_mov_b32_e32 v42, v127
	v_mov_b32_e32 v41, v127
	v_mov_b32_e32 v40, v127
	v_mov_b32_e32 v31, v127
	v_mov_b32_e32 v30, v127
	v_mov_b32_e32 v29, v127
	v_mov_b32_e32 v28, v127
	v_mov_b32_e32 v27, v127
	v_mov_b32_e32 v26, v127
	v_mov_b32_e32 v25, v127
	v_mov_b32_e32 v24, v127
	v_mov_b32_e32 v15, v127
	v_mov_b32_e32 v14, v127
	v_mov_b32_e32 v13, v127
	v_mov_b32_e32 v12, v127
	v_mov_b32_e32 v11, v127
	v_mov_b32_e32 v10, v127
	v_mov_b32_e32 v9, v127
	v_mov_b32_e32 v8, v127
	v_mov_b32_e32 v55, v127
	v_mov_b32_e32 v54, v127
	v_mov_b32_e32 v53, v127
	v_mov_b32_e32 v52, v127
	v_mov_b32_e32 v51, v127
	v_mov_b32_e32 v50, v127
	v_mov_b32_e32 v49, v127
	v_mov_b32_e32 v48, v127
	v_mov_b32_e32 v39, v127
	v_mov_b32_e32 v38, v127
	v_mov_b32_e32 v37, v127
	v_mov_b32_e32 v36, v127
	v_mov_b32_e32 v35, v127
	v_mov_b32_e32 v34, v127
	v_mov_b32_e32 v33, v127
	v_mov_b32_e32 v32, v127
	v_mov_b32_e32 v23, v127
	v_mov_b32_e32 v22, v127
	v_mov_b32_e32 v21, v127
	v_mov_b32_e32 v20, v127
	v_mov_b32_e32 v19, v127
	v_mov_b32_e32 v18, v127
	v_mov_b32_e32 v17, v127
	v_mov_b32_e32 v16, v127
	v_mov_b32_e32 v7, v127
	v_mov_b32_e32 v6, v127
	v_mov_b32_e32 v5, v127
	v_mov_b32_e32 v4, v127
	v_mov_b32_e32 v3, v127
	v_mov_b32_e32 v2, v127
	v_mov_b32_e32 v1, v127
	v_mov_b32_e32 v0, v127
	s_branch .LBB0_784
.Lzskip_6:
	s_add_u32 s4, s28, 0x80
	s_addc_u32 s5, s29, 0
	s_add_u32 s28, s24, 0x100
	v_mov_b32_e32 v0, 0
	s_addc_u32 s29, s25, 0
	s_mov_b32 s24, 0
	v_mov_b32_e32 v1, v0
	v_mov_b32_e32 v2, v0
	v_mov_b32_e32 v3, v0
	v_mov_b32_e32 v4, v0
	v_mov_b32_e32 v5, v0
	v_mov_b32_e32 v6, v0
	v_mov_b32_e32 v7, v0
	v_mov_b32_e32 v16, v0
	v_mov_b32_e32 v17, v0
	v_mov_b32_e32 v18, v0
	v_mov_b32_e32 v19, v0
	v_mov_b32_e32 v20, v0
	v_mov_b32_e32 v21, v0
	v_mov_b32_e32 v22, v0
	v_mov_b32_e32 v23, v0
	v_mov_b32_e32 v32, v0
	v_mov_b32_e32 v33, v0
	v_mov_b32_e32 v34, v0
	v_mov_b32_e32 v35, v0
	v_mov_b32_e32 v36, v0
	v_mov_b32_e32 v37, v0
	v_mov_b32_e32 v38, v0
	v_mov_b32_e32 v39, v0
	v_mov_b32_e32 v48, v0
	v_mov_b32_e32 v49, v0
	v_mov_b32_e32 v50, v0
	v_mov_b32_e32 v51, v0
	v_mov_b32_e32 v52, v0
	v_mov_b32_e32 v53, v0
	v_mov_b32_e32 v54, v0
	v_mov_b32_e32 v55, v0
	v_mov_b32_e32 v8, v0
	v_mov_b32_e32 v9, v0
	v_mov_b32_e32 v10, v0
	v_mov_b32_e32 v11, v0
	v_mov_b32_e32 v12, v0
	v_mov_b32_e32 v13, v0
	v_mov_b32_e32 v14, v0
	v_mov_b32_e32 v15, v0
	v_mov_b32_e32 v24, v0
	v_mov_b32_e32 v25, v0
	v_mov_b32_e32 v26, v0
	v_mov_b32_e32 v27, v0
	v_mov_b32_e32 v28, v0
	v_mov_b32_e32 v29, v0
	v_mov_b32_e32 v30, v0
	v_mov_b32_e32 v31, v0
	v_mov_b32_e32 v40, v0
	v_mov_b32_e32 v41, v0
	v_mov_b32_e32 v42, v0
	v_mov_b32_e32 v43, v0
	v_mov_b32_e32 v44, v0
	v_mov_b32_e32 v45, v0
	v_mov_b32_e32 v46, v0
	v_mov_b32_e32 v47, v0
	v_mov_b32_e32 v56, v0
	v_mov_b32_e32 v57, v0
	v_mov_b32_e32 v58, v0
	v_mov_b32_e32 v59, v0
	v_mov_b32_e32 v60, v0
	v_mov_b32_e32 v61, v0
	v_mov_b32_e32 v62, v0
	v_mov_b32_e32 v63, v0
	v_mov_b32_e32 v64, v0
	v_mov_b32_e32 v65, v0
	v_mov_b32_e32 v66, v0
	v_mov_b32_e32 v67, v0
	v_mov_b32_e32 v68, v0
	v_mov_b32_e32 v69, v0
	v_mov_b32_e32 v70, v0
	v_mov_b32_e32 v71, v0
	v_mov_b32_e32 v80, v0
	v_mov_b32_e32 v81, v0
	v_mov_b32_e32 v82, v0
	v_mov_b32_e32 v83, v0
	v_mov_b32_e32 v84, v0
	v_mov_b32_e32 v85, v0
	v_mov_b32_e32 v86, v0
	v_mov_b32_e32 v87, v0
	v_mov_b32_e32 v96, v0
	v_mov_b32_e32 v97, v0
	v_mov_b32_e32 v98, v0
	v_mov_b32_e32 v99, v0
	v_mov_b32_e32 v100, v0
	v_mov_b32_e32 v101, v0
	v_mov_b32_e32 v102, v0
	v_mov_b32_e32 v103, v0
	v_mov_b32_e32 v112, v0
	v_mov_b32_e32 v113, v0
	v_mov_b32_e32 v114, v0
	v_mov_b32_e32 v115, v0
	v_mov_b32_e32 v116, v0
	v_mov_b32_e32 v117, v0
	v_mov_b32_e32 v118, v0
	v_mov_b32_e32 v119, v0
	v_mov_b32_e32 v72, v0
	v_mov_b32_e32 v73, v0
	v_mov_b32_e32 v74, v0
	v_mov_b32_e32 v75, v0
	v_mov_b32_e32 v76, v0
	v_mov_b32_e32 v77, v0
	v_mov_b32_e32 v78, v0
	v_mov_b32_e32 v79, v0
	v_mov_b32_e32 v88, v0
	v_mov_b32_e32 v89, v0
	v_mov_b32_e32 v90, v0
	v_mov_b32_e32 v91, v0
	v_mov_b32_e32 v92, v0
	v_mov_b32_e32 v93, v0
	v_mov_b32_e32 v94, v0
	v_mov_b32_e32 v95, v0
	v_mov_b32_e32 v104, v0
	v_mov_b32_e32 v105, v0
	v_mov_b32_e32 v106, v0
	v_mov_b32_e32 v107, v0
	v_mov_b32_e32 v108, v0
	v_mov_b32_e32 v109, v0
	v_mov_b32_e32 v110, v0
	v_mov_b32_e32 v111, v0
	v_mov_b32_e32 v120, v0
	v_mov_b32_e32 v121, v0
	v_mov_b32_e32 v122, v0
	v_mov_b32_e32 v123, v0
	v_mov_b32_e32 v124, v0
	v_mov_b32_e32 v125, v0
	v_mov_b32_e32 v126, v0
	v_mov_b32_e32 v127, v0

.LBB0_1053:
	s_andn2_b64 vcc, exec, s[22:23]
	s_waitcnt lgkmcnt(0)
	s_cbranch_vccz .Lzskip_7
	v_mov_b32_e32 v123, 0
	v_mov_b32_e32 v122, v123
	v_mov_b32_e32 v121, v123
	v_mov_b32_e32 v120, v123
	v_mov_b32_e32 v127, v123
	v_mov_b32_e32 v126, v123
	v_mov_b32_e32 v125, v123
	v_mov_b32_e32 v124, v123
	v_mov_b32_e32 v111, v123
	v_mov_b32_e32 v110, v123
	v_mov_b32_e32 v109, v123
	v_mov_b32_e32 v108, v123
	v_mov_b32_e32 v107, v123
	v_mov_b32_e32 v106, v123
	v_mov_b32_e32 v105, v123
	v_mov_b32_e32 v104, v123
	v_mov_b32_e32 v95, v123
	v_mov_b32_e32 v94, v123
	v_mov_b32_e32 v93, v123
	v_mov_b32_e32 v92, v123
	v_mov_b32_e32 v91, v123
	v_mov_b32_e32 v90, v123
	v_mov_b32_e32 v89, v123
	v_mov_b32_e32 v88, v123
	v_mov_b32_e32 v79, v123
	v_mov_b32_e32 v78, v123
	v_mov_b32_e32 v77, v123
	v_mov_b32_e32 v76, v123
	v_mov_b32_e32 v75, v123
	v_mov_b32_e32 v74, v123
	v_mov_b32_e32 v73, v123
	v_mov_b32_e32 v72, v123
	v_mov_b32_e32 v119, v123
	v_mov_b32_e32 v118, v123
	v_mov_b32_e32 v117, v123
	v_mov_b32_e32 v116, v123
	v_mov_b32_e32 v115, v123
	v_mov_b32_e32 v114, v123
	v_mov_b32_e32 v113, v123
	v_mov_b32_e32 v112, v123
	v_mov_b32_e32 v103, v123
	v_mov_b32_e32 v102, v123
	v_mov_b32_e32 v101, v123
	v_mov_b32_e32 v100, v123
	v_mov_b32_e32 v99, v123
	v_mov_b32_e32 v98, v123
	v_mov_b32_e32 v97, v123
	v_mov_b32_e32 v96, v123
	v_mov_b32_e32 v87, v123
	v_mov_b32_e32 v86, v123
	v_mov_b32_e32 v85, v123
	v_mov_b32_e32 v84, v123
	v_mov_b32_e32 v83, v123
	v_mov_b32_e32 v82, v123
	v_mov_b32_e32 v81, v123
	v_mov_b32_e32 v80, v123
	v_mov_b32_e32 v71, v123
	v_mov_b32_e32 v70, v123
	v_mov_b32_e32 v69, v123
	v_mov_b32_e32 v68, v123
	v_mov_b32_e32 v67, v123
	v_mov_b32_e32 v66, v123
	v_mov_b32_e32 v65, v123
	v_mov_b32_e32 v64, v123
	v_mov_b32_e32 v63, v123
	v_mov_b32_e32 v62, v123
	v_mov_b32_e32 v61, v123
	v_mov_b32_e32 v60, v123
	v_mov_b32_e32 v59, v123
	v_mov_b32_e32 v58, v123
	v_mov_b32_e32 v57, v123
	v_mov_b32_e32 v56, v123
	v_mov_b32_e32 v47, v123
	v_mov_b32_e32 v46, v123
	v_mov_b32_e32 v45, v123
	v_mov_b32_e32 v44, v123
	v_mov_b32_e32 v43, v123
	v_mov_b32_e32 v42, v123
	v_mov_b32_e32 v41, v123
	v_mov_b32_e32 v40, v123
	v_mov_b32_e32 v31, v123
	v_mov_b32_e32 v30, v123
	v_mov_b32_e32 v29, v123
	v_mov_b32_e32 v28, v123
	v_mov_b32_e32 v27, v123
	v_mov_b32_e32 v26, v123
	v_mov_b32_e32 v25, v123
	v_mov_b32_e32 v24, v123
	v_mov_b32_e32 v15, v123
	v_mov_b32_e32 v14, v123
	v_mov_b32_e32 v13, v123
	v_mov_b32_e32 v12, v123
	v_mov_b32_e32 v11, v123
	v_mov_b32_e32 v10, v123
	v_mov_b32_e32 v9, v123
	v_mov_b32_e32 v8, v123
	v_mov_b32_e32 v55, v123
	v_mov_b32_e32 v54, v123
	v_mov_b32_e32 v53, v123
	v_mov_b32_e32 v52, v123
	v_mov_b32_e32 v51, v123
	v_mov_b32_e32 v50, v123
	v_mov_b32_e32 v49, v123
	v_mov_b32_e32 v48, v123
	v_mov_b32_e32 v39, v123
	v_mov_b32_e32 v38, v123
	v_mov_b32_e32 v37, v123
	v_mov_b32_e32 v36, v123
	v_mov_b32_e32 v35, v123
	v_mov_b32_e32 v34, v123
	v_mov_b32_e32 v33, v123
	v_mov_b32_e32 v32, v123
	v_mov_b32_e32 v23, v123
	v_mov_b32_e32 v22, v123
	v_mov_b32_e32 v21, v123
	v_mov_b32_e32 v20, v123
	v_mov_b32_e32 v19, v123
	v_mov_b32_e32 v18, v123
	v_mov_b32_e32 v17, v123
	v_mov_b32_e32 v16, v123
	v_mov_b32_e32 v7, v123
	v_mov_b32_e32 v6, v123
	v_mov_b32_e32 v5, v123
	v_mov_b32_e32 v4, v123
	v_mov_b32_e32 v3, v123
	v_mov_b32_e32 v2, v123
	v_mov_b32_e32 v1, v123
	v_mov_b32_e32 v0, v123
	s_branch .LBB0_1057
.Lzskip_7:
	s_add_u32 s24, s24, 0x80
	s_addc_u32 s25, s25, 0
	s_add_u32 s55, s28, 0x100
	v_mov_b32_e32 v0, 0
	s_addc_u32 s72, s29, 0
	s_mov_b32 s28, 0
	v_mov_b32_e32 v1, v0
	v_mov_b32_e32 v2, v0
	v_mov_b32_e32 v3, v0
	v_mov_b32_e32 v4, v0
	v_mov_b32_e32 v5, v0
	v_mov_b32_e32 v6, v0
	v_mov_b32_e32 v7, v0
	v_mov_b32_e32 v16, v0
	v_mov_b32_e32 v17, v0
	v_mov_b32_e32 v18, v0
	v_mov_b32_e32 v19, v0
	v_mov_b32_e32 v20, v0
	v_mov_b32_e32 v21, v0
	v_mov_b32_e32 v22, v0
	v_mov_b32_e32 v23, v0
	v_mov_b32_e32 v32, v0
	v_mov_b32_e32 v33, v0
	v_mov_b32_e32 v34, v0
	v_mov_b32_e32 v35, v0
	v_mov_b32_e32 v36, v0
	v_mov_b32_e32 v37, v0
	v_mov_b32_e32 v38, v0
	v_mov_b32_e32 v39, v0
	v_mov_b32_e32 v48, v0
	v_mov_b32_e32 v49, v0
	v_mov_b32_e32 v50, v0
	v_mov_b32_e32 v51, v0
	v_mov_b32_e32 v52, v0
	v_mov_b32_e32 v53, v0
	v_mov_b32_e32 v54, v0
	v_mov_b32_e32 v55, v0
	v_mov_b32_e32 v8, v0
	v_mov_b32_e32 v9, v0
	v_mov_b32_e32 v10, v0
	v_mov_b32_e32 v11, v0
	v_mov_b32_e32 v12, v0
	v_mov_b32_e32 v13, v0
	v_mov_b32_e32 v14, v0
	v_mov_b32_e32 v15, v0
	v_mov_b32_e32 v24, v0
	v_mov_b32_e32 v25, v0
	v_mov_b32_e32 v26, v0
	v_mov_b32_e32 v27, v0
	v_mov_b32_e32 v28, v0
	v_mov_b32_e32 v29, v0
	v_mov_b32_e32 v30, v0
	v_mov_b32_e32 v31, v0
	v_mov_b32_e32 v40, v0
	v_mov_b32_e32 v41, v0
	v_mov_b32_e32 v42, v0
	v_mov_b32_e32 v43, v0
	v_mov_b32_e32 v44, v0
	v_mov_b32_e32 v45, v0
	v_mov_b32_e32 v46, v0
	v_mov_b32_e32 v47, v0
	v_mov_b32_e32 v56, v0
	v_mov_b32_e32 v57, v0
	v_mov_b32_e32 v58, v0
	v_mov_b32_e32 v59, v0
	v_mov_b32_e32 v60, v0
	v_mov_b32_e32 v61, v0
	v_mov_b32_e32 v62, v0
	v_mov_b32_e32 v63, v0
	v_mov_b32_e32 v64, v0
	v_mov_b32_e32 v65, v0
	v_mov_b32_e32 v66, v0
	v_mov_b32_e32 v67, v0
	v_mov_b32_e32 v68, v0
	v_mov_b32_e32 v69, v0
	v_mov_b32_e32 v70, v0
	v_mov_b32_e32 v71, v0
	v_mov_b32_e32 v80, v0
	v_mov_b32_e32 v81, v0
	v_mov_b32_e32 v82, v0
	v_mov_b32_e32 v83, v0
	v_mov_b32_e32 v84, v0
	v_mov_b32_e32 v85, v0
	v_mov_b32_e32 v86, v0
	v_mov_b32_e32 v87, v0
	v_mov_b32_e32 v96, v0
	v_mov_b32_e32 v97, v0
	v_mov_b32_e32 v98, v0
	v_mov_b32_e32 v99, v0
	v_mov_b32_e32 v100, v0
	v_mov_b32_e32 v101, v0
	v_mov_b32_e32 v102, v0
	v_mov_b32_e32 v103, v0
	v_mov_b32_e32 v112, v0
	v_mov_b32_e32 v113, v0
	v_mov_b32_e32 v114, v0
	v_mov_b32_e32 v115, v0
	v_mov_b32_e32 v116, v0
	v_mov_b32_e32 v117, v0
	v_mov_b32_e32 v118, v0
	v_mov_b32_e32 v119, v0
	v_mov_b32_e32 v72, v0
	v_mov_b32_e32 v73, v0
	v_mov_b32_e32 v74, v0
	v_mov_b32_e32 v75, v0
	v_mov_b32_e32 v76, v0
	v_mov_b32_e32 v77, v0
	v_mov_b32_e32 v78, v0
	v_mov_b32_e32 v79, v0
	v_mov_b32_e32 v88, v0
	v_mov_b32_e32 v89, v0
	v_mov_b32_e32 v90, v0
	v_mov_b32_e32 v91, v0
	v_mov_b32_e32 v92, v0
	v_mov_b32_e32 v93, v0
	v_mov_b32_e32 v94, v0
	v_mov_b32_e32 v95, v0
	v_mov_b32_e32 v104, v0
	v_mov_b32_e32 v105, v0
	v_mov_b32_e32 v106, v0
	v_mov_b32_e32 v107, v0
	v_mov_b32_e32 v108, v0
	v_mov_b32_e32 v109, v0
	v_mov_b32_e32 v110, v0
	v_mov_b32_e32 v111, v0
	v_mov_b32_e32 v124, v0
	v_mov_b32_e32 v125, v0
	v_mov_b32_e32 v126, v0
	v_mov_b32_e32 v127, v0
	v_mov_b32_e32 v120, v0
	v_mov_b32_e32 v121, v0
	v_mov_b32_e32 v122, v0
	v_mov_b32_e32 v123, v0

.LBB0_1147:
	s_andn2_b64 vcc, exec, s[18:19]
	s_cbranch_vccz .Lzskip_8
	v_mov_b32_e32 v123, 0
	v_mov_b32_e32 v122, v123
	v_mov_b32_e32 v121, v123
	v_mov_b32_e32 v120, v123
	v_mov_b32_e32 v127, v123
	v_mov_b32_e32 v126, v123
	v_mov_b32_e32 v125, v123
	v_mov_b32_e32 v124, v123
	v_mov_b32_e32 v111, v123
	v_mov_b32_e32 v110, v123
	v_mov_b32_e32 v109, v123
	v_mov_b32_e32 v108, v123
	v_mov_b32_e32 v107, v123
	v_mov_b32_e32 v106, v123
	v_mov_b32_e32 v105, v123
	v_mov_b32_e32 v104, v123
	v_mov_b32_e32 v95, v123
	v_mov_b32_e32 v94, v123
	v_mov_b32_e32 v93, v123
	v_mov_b32_e32 v92, v123
	v_mov_b32_e32 v91, v123
	v_mov_b32_e32 v90, v123
	v_mov_b32_e32 v89, v123
	v_mov_b32_e32 v88, v123
	v_mov_b32_e32 v79, v123
	v_mov_b32_e32 v78, v123
	v_mov_b32_e32 v77, v123
	v_mov_b32_e32 v76, v123
	v_mov_b32_e32 v75, v123
	v_mov_b32_e32 v74, v123
	v_mov_b32_e32 v73, v123
	v_mov_b32_e32 v72, v123
	v_mov_b32_e32 v119, v123
	v_mov_b32_e32 v118, v123
	v_mov_b32_e32 v117, v123
	v_mov_b32_e32 v116, v123
	v_mov_b32_e32 v115, v123
	v_mov_b32_e32 v114, v123
	v_mov_b32_e32 v113, v123
	v_mov_b32_e32 v112, v123
	v_mov_b32_e32 v103, v123
	v_mov_b32_e32 v102, v123
	v_mov_b32_e32 v101, v123
	v_mov_b32_e32 v100, v123
	v_mov_b32_e32 v99, v123
	v_mov_b32_e32 v98, v123
	v_mov_b32_e32 v97, v123
	v_mov_b32_e32 v96, v123
	v_mov_b32_e32 v87, v123
	v_mov_b32_e32 v86, v123
	v_mov_b32_e32 v85, v123
	v_mov_b32_e32 v84, v123
	v_mov_b32_e32 v83, v123
	v_mov_b32_e32 v82, v123
	v_mov_b32_e32 v81, v123
	v_mov_b32_e32 v80, v123
	v_mov_b32_e32 v71, v123
	v_mov_b32_e32 v70, v123
	v_mov_b32_e32 v69, v123
	v_mov_b32_e32 v68, v123
	v_mov_b32_e32 v67, v123
	v_mov_b32_e32 v66, v123
	v_mov_b32_e32 v65, v123
	v_mov_b32_e32 v64, v123
	v_mov_b32_e32 v63, v123
	v_mov_b32_e32 v62, v123
	v_mov_b32_e32 v61, v123
	v_mov_b32_e32 v60, v123
	v_mov_b32_e32 v59, v123
	v_mov_b32_e32 v58, v123
	v_mov_b32_e32 v57, v123
	v_mov_b32_e32 v56, v123
	v_mov_b32_e32 v47, v123
	v_mov_b32_e32 v46, v123
	v_mov_b32_e32 v45, v123
	v_mov_b32_e32 v44, v123
	v_mov_b32_e32 v43, v123
	v_mov_b32_e32 v42, v123
	v_mov_b32_e32 v41, v123
	v_mov_b32_e32 v40, v123
	v_mov_b32_e32 v31, v123
	v_mov_b32_e32 v30, v123
	v_mov_b32_e32 v29, v123
	v_mov_b32_e32 v28, v123
	v_mov_b32_e32 v27, v123
	v_mov_b32_e32 v26, v123
	v_mov_b32_e32 v25, v123
	v_mov_b32_e32 v24, v123
	v_mov_b32_e32 v15, v123
	v_mov_b32_e32 v14, v123
	v_mov_b32_e32 v13, v123
	v_mov_b32_e32 v12, v123
	v_mov_b32_e32 v11, v123
	v_mov_b32_e32 v10, v123
	v_mov_b32_e32 v9, v123
	v_mov_b32_e32 v8, v123
	v_mov_b32_e32 v55, v123
	v_mov_b32_e32 v54, v123
	v_mov_b32_e32 v53, v123
	v_mov_b32_e32 v52, v123
	v_mov_b32_e32 v51, v123
	v_mov_b32_e32 v50, v123
	v_mov_b32_e32 v49, v123
	v_mov_b32_e32 v48, v123
	v_mov_b32_e32 v39, v123
	v_mov_b32_e32 v38, v123
	v_mov_b32_e32 v37, v123
	v_mov_b32_e32 v36, v123
	v_mov_b32_e32 v35, v123
	v_mov_b32_e32 v34, v123
	v_mov_b32_e32 v33, v123
	v_mov_b32_e32 v32, v123
	v_mov_b32_e32 v23, v123
	v_mov_b32_e32 v22, v123
	v_mov_b32_e32 v21, v123
	v_mov_b32_e32 v20, v123
	v_mov_b32_e32 v19, v123
	v_mov_b32_e32 v18, v123
	v_mov_b32_e32 v17, v123
	v_mov_b32_e32 v16, v123
	v_mov_b32_e32 v7, v123
	v_mov_b32_e32 v6, v123
	v_mov_b32_e32 v5, v123
	v_mov_b32_e32 v4, v123
	v_mov_b32_e32 v3, v123
	v_mov_b32_e32 v2, v123
	v_mov_b32_e32 v1, v123
	v_mov_b32_e32 v0, v123
	s_branch .LBB0_1151
.Lzskip_8:
	s_add_u32 s28, s28, 0x80
	s_addc_u32 s29, s29, 0
	s_add_u32 s48, s48, 0x100
	v_mov_b32_e32 v0, 0
	s_addc_u32 s49, s49, 0
	s_mov_b32 s30, 0
	v_mov_b32_e32 v1, v0
	v_mov_b32_e32 v2, v0
	v_mov_b32_e32 v3, v0
	v_mov_b32_e32 v4, v0
	v_mov_b32_e32 v5, v0
	v_mov_b32_e32 v6, v0
	v_mov_b32_e32 v7, v0
	v_mov_b32_e32 v16, v0
	v_mov_b32_e32 v17, v0
	v_mov_b32_e32 v18, v0
	v_mov_b32_e32 v19, v0
	v_mov_b32_e32 v20, v0
	v_mov_b32_e32 v21, v0
	v_mov_b32_e32 v22, v0
	v_mov_b32_e32 v23, v0
	v_mov_b32_e32 v32, v0
	v_mov_b32_e32 v33, v0
	v_mov_b32_e32 v34, v0
	v_mov_b32_e32 v35, v0
	v_mov_b32_e32 v36, v0
	v_mov_b32_e32 v37, v0
	v_mov_b32_e32 v38, v0
	v_mov_b32_e32 v39, v0
	v_mov_b32_e32 v48, v0
	v_mov_b32_e32 v49, v0
	v_mov_b32_e32 v50, v0
	v_mov_b32_e32 v51, v0
	v_mov_b32_e32 v52, v0
	v_mov_b32_e32 v53, v0
	v_mov_b32_e32 v54, v0
	v_mov_b32_e32 v55, v0
	v_mov_b32_e32 v8, v0
	v_mov_b32_e32 v9, v0
	v_mov_b32_e32 v10, v0
	v_mov_b32_e32 v11, v0
	v_mov_b32_e32 v12, v0
	v_mov_b32_e32 v13, v0
	v_mov_b32_e32 v14, v0
	v_mov_b32_e32 v15, v0
	v_mov_b32_e32 v24, v0
	v_mov_b32_e32 v25, v0
	v_mov_b32_e32 v26, v0
	v_mov_b32_e32 v27, v0
	v_mov_b32_e32 v28, v0
	v_mov_b32_e32 v29, v0
	v_mov_b32_e32 v30, v0
	v_mov_b32_e32 v31, v0
	v_mov_b32_e32 v40, v0
	v_mov_b32_e32 v41, v0
	v_mov_b32_e32 v42, v0
	v_mov_b32_e32 v43, v0
	v_mov_b32_e32 v44, v0
	v_mov_b32_e32 v45, v0
	v_mov_b32_e32 v46, v0
	v_mov_b32_e32 v47, v0
	v_mov_b32_e32 v56, v0
	v_mov_b32_e32 v57, v0
	v_mov_b32_e32 v58, v0
	v_mov_b32_e32 v59, v0
	v_mov_b32_e32 v60, v0
	v_mov_b32_e32 v61, v0
	v_mov_b32_e32 v62, v0
	v_mov_b32_e32 v63, v0
	v_mov_b32_e32 v64, v0
	v_mov_b32_e32 v65, v0
	v_mov_b32_e32 v66, v0
	v_mov_b32_e32 v67, v0
	v_mov_b32_e32 v68, v0
	v_mov_b32_e32 v69, v0
	v_mov_b32_e32 v70, v0
	v_mov_b32_e32 v71, v0
	v_mov_b32_e32 v80, v0
	v_mov_b32_e32 v81, v0
	v_mov_b32_e32 v82, v0
	v_mov_b32_e32 v83, v0
	v_mov_b32_e32 v84, v0
	v_mov_b32_e32 v85, v0
	v_mov_b32_e32 v86, v0
	v_mov_b32_e32 v87, v0
	v_mov_b32_e32 v96, v0
	v_mov_b32_e32 v97, v0
	v_mov_b32_e32 v98, v0
	v_mov_b32_e32 v99, v0
	v_mov_b32_e32 v100, v0
	v_mov_b32_e32 v101, v0
	v_mov_b32_e32 v102, v0
	v_mov_b32_e32 v103, v0
	v_mov_b32_e32 v112, v0
	v_mov_b32_e32 v113, v0
	v_mov_b32_e32 v114, v0
	v_mov_b32_e32 v115, v0
	v_mov_b32_e32 v116, v0
	v_mov_b32_e32 v117, v0
	v_mov_b32_e32 v118, v0
	v_mov_b32_e32 v119, v0
	v_mov_b32_e32 v72, v0
	v_mov_b32_e32 v73, v0
	v_mov_b32_e32 v74, v0
	v_mov_b32_e32 v75, v0
	v_mov_b32_e32 v76, v0
	v_mov_b32_e32 v77, v0
	v_mov_b32_e32 v78, v0
	v_mov_b32_e32 v79, v0
	v_mov_b32_e32 v88, v0
	v_mov_b32_e32 v89, v0
	v_mov_b32_e32 v90, v0
	v_mov_b32_e32 v91, v0
	v_mov_b32_e32 v92, v0
	v_mov_b32_e32 v93, v0
	v_mov_b32_e32 v94, v0
	v_mov_b32_e32 v95, v0
	v_mov_b32_e32 v104, v0
	v_mov_b32_e32 v105, v0
	v_mov_b32_e32 v106, v0
	v_mov_b32_e32 v107, v0
	v_mov_b32_e32 v108, v0
	v_mov_b32_e32 v109, v0
	v_mov_b32_e32 v110, v0
	v_mov_b32_e32 v111, v0
	v_mov_b32_e32 v124, v0
	v_mov_b32_e32 v125, v0
	v_mov_b32_e32 v126, v0
	v_mov_b32_e32 v127, v0
	v_mov_b32_e32 v120, v0
	v_mov_b32_e32 v121, v0
	v_mov_b32_e32 v122, v0
	v_mov_b32_e32 v123, v0

.LBB0_1224:
	s_andn2_b64 vcc, exec, s[22:23]
	s_waitcnt lgkmcnt(0)
	s_cbranch_vccz .Lzskip_9
	v_mov_b32_e32 v127, 0
	v_mov_b32_e32 v126, v127
	v_mov_b32_e32 v125, v127
	v_mov_b32_e32 v124, v127
	v_mov_b32_e32 v123, v127
	v_mov_b32_e32 v122, v127
	v_mov_b32_e32 v121, v127
	v_mov_b32_e32 v120, v127
	v_mov_b32_e32 v111, v127
	v_mov_b32_e32 v110, v127
	v_mov_b32_e32 v109, v127
	v_mov_b32_e32 v108, v127
	v_mov_b32_e32 v107, v127
	v_mov_b32_e32 v106, v127
	v_mov_b32_e32 v105, v127
	v_mov_b32_e32 v104, v127
	v_mov_b32_e32 v95, v127
	v_mov_b32_e32 v94, v127
	v_mov_b32_e32 v93, v127
	v_mov_b32_e32 v92, v127
	v_mov_b32_e32 v91, v127
	v_mov_b32_e32 v90, v127
	v_mov_b32_e32 v89, v127
	v_mov_b32_e32 v88, v127
	v_mov_b32_e32 v79, v127
	v_mov_b32_e32 v78, v127
	v_mov_b32_e32 v77, v127
	v_mov_b32_e32 v76, v127
	v_mov_b32_e32 v75, v127
	v_mov_b32_e32 v74, v127
	v_mov_b32_e32 v73, v127
	v_mov_b32_e32 v72, v127
	v_mov_b32_e32 v119, v127
	v_mov_b32_e32 v118, v127
	v_mov_b32_e32 v117, v127
	v_mov_b32_e32 v116, v127
	v_mov_b32_e32 v115, v127
	v_mov_b32_e32 v114, v127
	v_mov_b32_e32 v113, v127
	v_mov_b32_e32 v112, v127
	v_mov_b32_e32 v103, v127
	v_mov_b32_e32 v102, v127
	v_mov_b32_e32 v101, v127
	v_mov_b32_e32 v100, v127
	v_mov_b32_e32 v99, v127
	v_mov_b32_e32 v98, v127
	v_mov_b32_e32 v97, v127
	v_mov_b32_e32 v96, v127
	v_mov_b32_e32 v87, v127
	v_mov_b32_e32 v86, v127
	v_mov_b32_e32 v85, v127
	v_mov_b32_e32 v84, v127
	v_mov_b32_e32 v83, v127
	v_mov_b32_e32 v82, v127
	v_mov_b32_e32 v81, v127
	v_mov_b32_e32 v80, v127
	v_mov_b32_e32 v71, v127
	v_mov_b32_e32 v70, v127
	v_mov_b32_e32 v69, v127
	v_mov_b32_e32 v68, v127
	v_mov_b32_e32 v67, v127
	v_mov_b32_e32 v66, v127
	v_mov_b32_e32 v65, v127
	v_mov_b32_e32 v64, v127
	v_mov_b32_e32 v63, v127
	v_mov_b32_e32 v62, v127
	v_mov_b32_e32 v61, v127
	v_mov_b32_e32 v60, v127
	v_mov_b32_e32 v59, v127
	v_mov_b32_e32 v58, v127
	v_mov_b32_e32 v57, v127
	v_mov_b32_e32 v56, v127
	v_mov_b32_e32 v47, v127
	v_mov_b32_e32 v46, v127
	v_mov_b32_e32 v45, v127
	v_mov_b32_e32 v44, v127
	v_mov_b32_e32 v43, v127
	v_mov_b32_e32 v42, v127
	v_mov_b32_e32 v41, v127
	v_mov_b32_e32 v40, v127
	v_mov_b32_e32 v31, v127
	v_mov_b32_e32 v30, v127
	v_mov_b32_e32 v29, v127
	v_mov_b32_e32 v28, v127
	v_mov_b32_e32 v27, v127
	v_mov_b32_e32 v26, v127
	v_mov_b32_e32 v25, v127
	v_mov_b32_e32 v24, v127
	v_mov_b32_e32 v15, v127
	v_mov_b32_e32 v14, v127
	v_mov_b32_e32 v13, v127
	v_mov_b32_e32 v12, v127
	v_mov_b32_e32 v11, v127
	v_mov_b32_e32 v10, v127
	v_mov_b32_e32 v9, v127
	v_mov_b32_e32 v8, v127
	v_mov_b32_e32 v55, v127
	v_mov_b32_e32 v54, v127
	v_mov_b32_e32 v53, v127
	v_mov_b32_e32 v52, v127
	v_mov_b32_e32 v51, v127
	v_mov_b32_e32 v50, v127
	v_mov_b32_e32 v49, v127
	v_mov_b32_e32 v48, v127
	v_mov_b32_e32 v39, v127
	v_mov_b32_e32 v38, v127
	v_mov_b32_e32 v37, v127
	v_mov_b32_e32 v36, v127
	v_mov_b32_e32 v35, v127
	v_mov_b32_e32 v34, v127
	v_mov_b32_e32 v33, v127
	v_mov_b32_e32 v32, v127
	v_mov_b32_e32 v23, v127
	v_mov_b32_e32 v22, v127
	v_mov_b32_e32 v21, v127
	v_mov_b32_e32 v20, v127
	v_mov_b32_e32 v19, v127
	v_mov_b32_e32 v18, v127
	v_mov_b32_e32 v17, v127
	v_mov_b32_e32 v16, v127
	v_mov_b32_e32 v7, v127
	v_mov_b32_e32 v6, v127
	v_mov_b32_e32 v5, v127
	v_mov_b32_e32 v4, v127
	v_mov_b32_e32 v3, v127
	v_mov_b32_e32 v2, v127
	v_mov_b32_e32 v1, v127
	v_mov_b32_e32 v0, v127
	s_branch .LBB0_1227
.Lzskip_9:
	s_add_u32 s0, s24, 0x80
	s_addc_u32 s1, s25, 0
	s_add_u32 s24, s10, 0x100
	v_mov_b32_e32 v0, 0
	s_addc_u32 s25, s11, 0
	s_mov_b32 s10, 0
	v_mov_b32_e32 v1, v0
	v_mov_b32_e32 v2, v0
	v_mov_b32_e32 v3, v0
	v_mov_b32_e32 v4, v0
	v_mov_b32_e32 v5, v0
	v_mov_b32_e32 v6, v0
	v_mov_b32_e32 v7, v0
	v_mov_b32_e32 v16, v0
	v_mov_b32_e32 v17, v0
	v_mov_b32_e32 v18, v0
	v_mov_b32_e32 v19, v0
	v_mov_b32_e32 v20, v0
	v_mov_b32_e32 v21, v0
	v_mov_b32_e32 v22, v0
	v_mov_b32_e32 v23, v0
	v_mov_b32_e32 v32, v0
	v_mov_b32_e32 v33, v0
	v_mov_b32_e32 v34, v0
	v_mov_b32_e32 v35, v0
	v_mov_b32_e32 v36, v0
	v_mov_b32_e32 v37, v0
	v_mov_b32_e32 v38, v0
	v_mov_b32_e32 v39, v0
	v_mov_b32_e32 v48, v0
	v_mov_b32_e32 v49, v0
	v_mov_b32_e32 v50, v0
	v_mov_b32_e32 v51, v0
	v_mov_b32_e32 v52, v0
	v_mov_b32_e32 v53, v0
	v_mov_b32_e32 v54, v0
	v_mov_b32_e32 v55, v0
	v_mov_b32_e32 v8, v0
	v_mov_b32_e32 v9, v0
	v_mov_b32_e32 v10, v0
	v_mov_b32_e32 v11, v0
	v_mov_b32_e32 v12, v0
	v_mov_b32_e32 v13, v0
	v_mov_b32_e32 v14, v0
	v_mov_b32_e32 v15, v0
	v_mov_b32_e32 v24, v0
	v_mov_b32_e32 v25, v0
	v_mov_b32_e32 v26, v0
	v_mov_b32_e32 v27, v0
	v_mov_b32_e32 v28, v0
	v_mov_b32_e32 v29, v0
	v_mov_b32_e32 v30, v0
	v_mov_b32_e32 v31, v0
	v_mov_b32_e32 v40, v0
	v_mov_b32_e32 v41, v0
	v_mov_b32_e32 v42, v0
	v_mov_b32_e32 v43, v0
	v_mov_b32_e32 v44, v0
	v_mov_b32_e32 v45, v0
	v_mov_b32_e32 v46, v0
	v_mov_b32_e32 v47, v0
	v_mov_b32_e32 v56, v0
	v_mov_b32_e32 v57, v0
	v_mov_b32_e32 v58, v0
	v_mov_b32_e32 v59, v0
	v_mov_b32_e32 v60, v0
	v_mov_b32_e32 v61, v0
	v_mov_b32_e32 v62, v0
	v_mov_b32_e32 v63, v0
	v_mov_b32_e32 v64, v0
	v_mov_b32_e32 v65, v0
	v_mov_b32_e32 v66, v0
	v_mov_b32_e32 v67, v0
	v_mov_b32_e32 v68, v0
	v_mov_b32_e32 v69, v0
	v_mov_b32_e32 v70, v0
	v_mov_b32_e32 v71, v0
	v_mov_b32_e32 v80, v0
	v_mov_b32_e32 v81, v0
	v_mov_b32_e32 v82, v0
	v_mov_b32_e32 v83, v0
	v_mov_b32_e32 v84, v0
	v_mov_b32_e32 v85, v0
	v_mov_b32_e32 v86, v0
	v_mov_b32_e32 v87, v0
	v_mov_b32_e32 v96, v0
	v_mov_b32_e32 v97, v0
	v_mov_b32_e32 v98, v0
	v_mov_b32_e32 v99, v0
	v_mov_b32_e32 v100, v0
	v_mov_b32_e32 v101, v0
	v_mov_b32_e32 v102, v0
	v_mov_b32_e32 v103, v0
	v_mov_b32_e32 v112, v0
	v_mov_b32_e32 v113, v0
	v_mov_b32_e32 v114, v0
	v_mov_b32_e32 v115, v0
	v_mov_b32_e32 v116, v0
	v_mov_b32_e32 v117, v0
	v_mov_b32_e32 v118, v0
	v_mov_b32_e32 v119, v0
	v_mov_b32_e32 v72, v0
	v_mov_b32_e32 v73, v0
	v_mov_b32_e32 v74, v0
	v_mov_b32_e32 v75, v0
	v_mov_b32_e32 v76, v0
	v_mov_b32_e32 v77, v0
	v_mov_b32_e32 v78, v0
	v_mov_b32_e32 v79, v0
	v_mov_b32_e32 v88, v0
	v_mov_b32_e32 v89, v0
	v_mov_b32_e32 v90, v0
	v_mov_b32_e32 v91, v0
	v_mov_b32_e32 v92, v0
	v_mov_b32_e32 v93, v0
	v_mov_b32_e32 v94, v0
	v_mov_b32_e32 v95, v0
	v_mov_b32_e32 v104, v0
	v_mov_b32_e32 v105, v0
	v_mov_b32_e32 v106, v0
	v_mov_b32_e32 v107, v0
	v_mov_b32_e32 v108, v0
	v_mov_b32_e32 v109, v0
	v_mov_b32_e32 v110, v0
	v_mov_b32_e32 v111, v0
	v_mov_b32_e32 v120, v0
	v_mov_b32_e32 v121, v0
	v_mov_b32_e32 v122, v0
	v_mov_b32_e32 v123, v0
	v_mov_b32_e32 v124, v0
	v_mov_b32_e32 v125, v0
	v_mov_b32_e32 v126, v0
	v_mov_b32_e32 v127, v0
